# strategy #6 LDS bank conflicts: retB group-norm transpose tile padded (row stride 161, 8-float pad per 32-column segment) so the per-(row,segment) readers are conflict-free
# baseline (speedup 1.0000x reference)
.LBB0_586:
	v_add_u32_e32 v157, v161, v127
	v_sub_u32_e32 v158, v127, v89
	v_sub_u32_e32 v193, v127, v88
	v_sub_u32_e32 v204, v127, v91
	v_sub_u32_e32 v210, v127, v90
	v_sub_u32_e32 v211, v127, v93
	v_sub_u32_e32 v212, v127, v92
	v_sub_u32_e32 v213, v127, v95
	v_sub_u32_e32 v214, v127, v94
	v_cvt_f32_u32_e32 v39, v157
	v_cvt_f32_u32_e32 v40, v193
	v_cvt_f32_u32_e32 v41, v158
	v_cvt_f32_u32_e32 v42, v210
	v_cvt_f32_u32_e32 v43, v204
	v_cvt_f32_u32_e32 v44, v212
	v_cvt_f32_u32_e32 v45, v211
	v_cvt_f32_u32_e32 v46, v214
	v_cvt_f32_u32_e32 v47, v213
	ds_read_b128 v[32:35], v115
	ds_read_b128 v[172:175], v115 offset:32
	ds_read_b128 v[176:179], v115 offset:64
	ds_read_b128 v[180:183], v115 offset:96
	v_add_u32_e32 v36, 0xffffdc00, v156
	v_add_u32_e32 v37, 0xfffffc00, v156
	v_add_u32_e32 v38, 0xffffe000, v156
	ds_read_b64_tr_b16 v[188:189], v36
	ds_read_b64_tr_b16 v[190:191], v36 offset:512
	ds_read_b64_tr_b16 v[184:185], v37
	ds_read_b64_tr_b16 v[186:187], v37 offset:512
	s_waitcnt lgkmcnt(0)
	ds_read_b64_tr_b16 v[198:199], v38
	ds_read_b64_tr_b16 v[200:201], v38 offset:512
	ds_read_b64_tr_b16 v[194:195], v156
	ds_read_b64_tr_b16 v[196:197], v156 offset:512
	s_waitcnt lgkmcnt(0)
	v_mul_f32_e32 v223, v151, v39
	v_mul_f32_e32 v224, v151, v40
	v_mul_f32_e32 v225, v151, v41
	v_mul_f32_e32 v231, v151, v42
	v_mul_f32_e32 v232, v151, v43
	v_mul_f32_e32 v233, v151, v44
	v_mul_f32_e32 v234, v151, v45
	v_mul_f32_e32 v235, v151, v46
	v_mul_f32_e32 v236, v151, v47
	s_waitcnt lgkmcnt(3)
	v_mfma_f32_32x32x16_bf16 v[32:47], v[32:35], v[72:75], 0
	v_add_u32_e32 v221, -1, v157
	v_sub_u32_e32 v215, v127, v97
	v_sub_u32_e32 v216, v127, v96
	v_sub_u32_e32 v217, v127, v99
	v_sub_u32_e32 v218, v127, v98
	v_sub_u32_e32 v219, v127, v101
	v_sub_u32_e32 v220, v127, v100
	s_waitcnt lgkmcnt(2)
	v_mfma_f32_32x32x16_bf16 v[32:47], v[172:175], v[76:79], v[32:47]
	v_cvt_f32_u32_e32 v222, v221
	v_cvt_f32_u32_e32 v202, v216
	v_cvt_f32_u32_e32 v203, v215
	v_cvt_f32_u32_e32 v206, v218
	v_cvt_f32_u32_e32 v207, v217
	v_cvt_f32_u32_e32 v208, v220
	v_cvt_f32_u32_e32 v209, v219
	s_waitcnt lgkmcnt(1)
	v_mfma_f32_32x32x16_bf16 v[32:47], v[176:179], v[80:83], v[32:47]
	v_mul_f32_e32 v222, v151, v222
	v_mul_f32_e32 v237, v151, v202
	v_mul_f32_e32 v238, v151, v203
	v_mul_f32_e32 v239, v151, v206
	v_mul_f32_e32 v240, v151, v207
	v_mul_f32_e32 v208, v151, v208
	v_mul_f32_e32 v209, v151, v209
	s_waitcnt lgkmcnt(0)
	v_mfma_f32_32x32x16_bf16 v[32:47], v[180:183], v[84:87], v[32:47]
	v_exp_f32_e32 v223, v223
	v_exp_f32_e32 v202, v224
	v_exp_f32_e32 v203, v225
	v_exp_f32_e32 v172, v231
	v_exp_f32_e32 v173, v232
	v_exp_f32_e32 v174, v233
	v_exp_f32_e32 v175, v234
	v_exp_f32_e32 v222, v222
	v_exp_f32_e32 v206, v235
	v_exp_f32_e32 v207, v236
	v_exp_f32_e32 v176, v237
	v_exp_f32_e32 v177, v238
	v_exp_f32_e32 v178, v239
	v_exp_f32_e32 v179, v240
	v_exp_f32_e32 v208, v208
	v_exp_f32_e32 v209, v209
	v_mul_f32_e32 v180, v223, v32
	v_mul_f32_e32 v181, v222, v33
	v_cmp_lt_i32_e32 vcc, -1, v221
	v_pk_mul_f32 v[32:33], v[202:203], v[34:35]
	v_pk_mul_f32 v[34:35], v[172:173], v[36:37]
	v_pk_mul_f32 v[36:37], v[174:175], v[38:39]
	v_pk_mul_f32 v[38:39], v[206:207], v[40:41]
	v_pk_mul_f32 v[40:41], v[176:177], v[42:43]
	v_pk_mul_f32 v[42:43], v[178:179], v[44:45]
	v_pk_mul_f32 v[44:45], v[208:209], v[46:47]
	v_cmp_lt_i32_e64 s[0:1], -1, v157
	v_cndmask_b32_e32 v47, 0, v181, vcc
	v_cvt_pk_bf16_f32 v33, v32, v33
	v_cmp_lt_i32_e32 vcc, -1, v193
	v_cvt_pk_bf16_f32 v34, v34, v35
	v_cvt_pk_bf16_f32 v35, v36, v37
	v_cndmask_b32_e64 v46, 0, v180, s[0:1]
	v_cmp_lt_i32_e64 s[0:1], -1, v210
	v_cmp_lt_i32_e64 s[4:5], -1, v212
	v_cvt_pk_bf16_f32 v36, v38, v39
	v_cvt_pk_bf16_f32 v37, v40, v41
	v_cvt_pk_bf16_f32 v39, v44, v45
	v_lshrrev_b32_e32 v40, 16, v34
	v_cmp_lt_i32_e64 s[14:15], -1, v204
	v_lshrrev_b32_e32 v41, 16, v35
	v_cmp_lt_i32_e64 s[16:17], -1, v211
	v_cndmask_b32_e32 v45, 0, v33, vcc
	v_lshrrev_b32_e32 v33, 16, v33
	v_cmp_lt_i32_e32 vcc, -1, v158
	v_cndmask_b32_e64 v34, 0, v34, s[0:1]
	v_cndmask_b32_e64 v35, 0, v35, s[4:5]
	v_cndmask_b32_e32 v33, 0, v33, vcc
	v_cndmask_b32_e64 v40, 0, v40, s[14:15]
	v_cndmask_b32_e64 v41, 0, v41, s[16:17]
	v_cvt_pk_bf16_f32 v32, v46, v47
	v_perm_b32 v33, v33, v45, s29
	v_perm_b32 v34, v40, v34, s29
	v_perm_b32 v35, v41, v35, s29
	v_cmp_lt_i32_e64 s[6:7], -1, v214
	v_cvt_pk_bf16_f32 v38, v42, v43
	v_mfma_f32_32x32x16_bf16 v[0:15], v[188:191], v[32:35], v[0:15]
	v_cmp_lt_i32_e64 s[8:9], -1, v216
	v_cmp_lt_i32_e64 s[10:11], -1, v218
	v_cmp_lt_i32_e64 s[12:13], -1, v220
	v_lshrrev_b32_e32 v42, 16, v37
	v_cmp_lt_i32_e64 s[18:19], -1, v215
	v_lshrrev_b32_e32 v43, 16, v38
	v_cmp_lt_i32_e64 s[20:21], -1, v217
	v_mfma_f32_32x32x16_bf16 v[16:31], v[184:187], v[32:35], v[16:31]
	v_lshrrev_b32_e32 v44, 16, v39
	v_cmp_lt_i32_e64 s[22:23], -1, v219
	v_cndmask_b32_e64 v40, 0, v36, s[6:7]
	v_lshrrev_b32_e32 v36, 16, v36
	v_cmp_lt_i32_e32 vcc, -1, v213
	v_cndmask_b32_e64 v37, 0, v37, s[8:9]
	v_cndmask_b32_e64 v38, 0, v38, s[10:11]
	v_cndmask_b32_e64 v39, 0, v39, s[12:13]
	v_cndmask_b32_e32 v36, 0, v36, vcc
	v_cndmask_b32_e64 v33, 0, v42, s[18:19]
	v_cndmask_b32_e64 v34, 0, v43, s[20:21]
	v_cndmask_b32_e64 v35, 0, v44, s[22:23]
	v_perm_b32 v32, v36, v40, s29
	v_perm_b32 v33, v33, v37, s29
	v_perm_b32 v34, v34, v38, s29
	v_perm_b32 v35, v35, v39, s29
	s_add_i32 s33, s33, -1
	v_subrev_u32_e32 v127, 32, v127
	v_mfma_f32_32x32x16_bf16 v[0:15], v[198:201], v[32:35], v[0:15]
	v_add_u32_e32 v115, 0x1200, v115
	s_cmp_lg_u32 s33, 0
	v_add_u32_e32 v156, 0x800, v156
	v_mfma_f32_32x32x16_bf16 v[16:31], v[194:197], v[32:35], v[16:31]
	s_cbranch_scc1 .LBB0_586
	v_or_b32_e32 v32, s41, v228
	s_movk_i32 s0, 0x284
	v_mul_lo_u32 v32, v32, s0
	s_mul_i32 s0, s3, 0x140
	s_add_i32 s0, s0, 0
	v_add_u32_e32 v32, s0, v32
	v_add_u32_e32 v172, v32, v126
	s_waitcnt lgkmcnt(0)
	s_barrier
	ds_write2_b32 v172, v0, v1 offset1:1
	ds_write2_b32 v172, v2, v3 offset0:2 offset1:3
	ds_write2_b32 v172, v4, v5 offset0:8 offset1:9
	ds_write2_b32 v172, v6, v7 offset0:10 offset1:11
	ds_write2_b32 v172, v8, v9 offset0:16 offset1:17
	ds_write2_b32 v172, v10, v11 offset0:18 offset1:19
	ds_write2_b32 v172, v12, v13 offset0:24 offset1:25
	ds_write2_b32 v172, v14, v15 offset0:26 offset1:27
	ds_write2_b32 v172, v16, v17 offset0:40 offset1:41
	ds_write2_b32 v172, v18, v19 offset0:42 offset1:43
	ds_write2_b32 v172, v20, v21 offset0:48 offset1:49
	ds_write2_b32 v172, v22, v23 offset0:50 offset1:51
	ds_write2_b32 v172, v24, v25 offset0:56 offset1:57
	ds_write2_b32 v172, v26, v27 offset0:58 offset1:59
	ds_write2_b32 v172, v28, v29 offset0:64 offset1:65
	ds_write2_b32 v172, v30, v31 offset0:66 offset1:67
	v_mul_u32_u24_e32 v0, 0x284, v112
	v_lshlrev_b32_e32 v32, 2, v121
	v_mad_u32_u24 v158, v121, 5, v0
	v_mbcnt_lo_u32_b32 v0, -1, 0
	v_mbcnt_hi_u32_b32 v182, -1, v0
	v_and_b32_e32 v1, 64, v182
	v_xor_b32_e32 v0, 1, v182
	v_add_u32_e32 v183, 64, v1
	v_cmp_lt_i32_e32 vcc, v0, v183
	s_lshl_b32 s0, s36, 2
	s_add_u32 s0, s72, s0
	v_cndmask_b32_e32 v0, v182, v0, vcc
	v_lshlrev_b32_e32 v157, 2, v0
	v_xor_b32_e32 v0, 2, v182
	v_cmp_lt_i32_e32 vcc, v0, v183
	s_waitcnt lgkmcnt(0)
	s_barrier
	s_addc_u32 s1, s73, 0
	v_cndmask_b32_e32 v0, v182, v0, vcc
	v_mov_b32_e32 v33, 0
	v_readlane_b32 s4, v254, 0
	v_lshlrev_b32_e32 v156, 2, v0
	v_lshl_add_u64 v[80:81], s[0:1], 0, v[32:33]
	global_load_dwordx4 v[16:19], v32, s[0:1] offset:48
	global_load_dwordx4 v[20:23], v32, s[0:1] offset:32
	global_load_dwordx4 v[24:27], v32, s[0:1] offset:16
	global_load_dwordx4 v[28:31], v32, s[0:1]
	global_load_dwordx4 v[0:3], v32, s[0:1] offset:112
	global_load_dwordx4 v[4:7], v32, s[0:1] offset:96
	global_load_dwordx4 v[8:11], v32, s[0:1] offset:80
	global_load_dwordx4 v[12:15], v32, s[0:1] offset:64
	s_lshl_b64 s[0:1], s[34:35], 12
	v_readlane_b32 s6, v254, 2
	v_readlane_b32 s7, v254, 3
	s_add_u32 s0, s6, s0
	v_lshlrev_b32_e32 v32, 11, v119
	s_addc_u32 s1, s7, s1
	v_and_b32_e32 v32, 0x7f800, v32
	v_lshl_add_u64 v[34:35], s[0:1], 0, v[32:33]
	v_lshlrev_b32_e32 v32, 16, v70
	v_and_b32_e32 v38, 0xffff0000, v70
	v_mul_f32_e32 v36, 0xbfb8aa3b, v32
	v_mul_f32_e32 v37, 0xbfb8aa3b, v38
	v_exp_f32_e32 v36, v36
	v_exp_f32_e32 v37, v37
	v_lshlrev_b32_e32 v45, 16, v69
	v_and_b32_e32 v46, 0xffff0000, v69
	v_lshlrev_b32_e32 v74, 16, v71
	v_pk_add_f32 v[36:37], v[36:37], 1.0 op_sel_hi:[1,0]
	v_and_b32_e32 v44, 0xffff0000, v71
	v_lshlrev_b32_e32 v79, 16, v66
	v_and_b32_e32 v66, 0xffff0000, v66
	v_lshlrev_b32_e32 v119, 16, v67
	v_rcp_f32_e32 v39, v37
	s_nop 0
	v_mul_f32_e32 v37, v38, v39
	v_mul_f32_e32 v39, 0xbfb8aa3b, v46
	v_mul_f32_e32 v38, 0xbfb8aa3b, v45
	v_exp_f32_e32 v38, v38
	v_exp_f32_e32 v39, v39
	s_nop 0
	v_pk_add_f32 v[38:39], v[38:39], 1.0 op_sel_hi:[1,0]
	v_rcp_f32_e32 v40, v36
	s_nop 0
	v_mul_f32_e32 v36, v32, v40
	v_and_b32_e32 v86, 0xffff0000, v67
	v_rcp_f32_e32 v32, v39
	s_nop 0
	v_mul_f32_e32 v39, v46, v32
	v_lshlrev_b32_e32 v87, 16, v65
	v_lshlrev_b32_e32 v42, 16, v68
	v_and_b32_e32 v43, 0xffff0000, v68
	v_mul_f32_e32 v40, 0xbfb8aa3b, v42
	v_mul_f32_e32 v41, 0xbfb8aa3b, v43
	v_exp_f32_e32 v40, v40
	v_exp_f32_e32 v41, v41
	v_rcp_f32_e32 v32, v38
	s_nop 0
	v_mul_f32_e32 v38, v45, v32
	v_and_b32_e32 v65, 0xffff0000, v65
	v_lshlrev_b32_e32 v121, 16, v64
	v_pk_add_f32 v[40:41], v[40:41], 1.0 op_sel_hi:[1,0]
	v_and_b32_e32 v126, 0xffff0000, v64
	v_mul_f32_e32 v64, 0xbfb8aa3b, v121
	v_lshlrev_b32_e32 v174, 16, v62
	v_and_b32_e32 v62, 0xffff0000, v62
	v_rcp_f32_e32 v45, v41
	s_nop 0
	v_mul_f32_e32 v41, v43, v45
	v_lshlrev_b32_e32 v184, 16, v60
	v_rcp_f32_e32 v43, v40
	s_nop 0
	v_mul_f32_e32 v40, v42, v43
	v_mul_f32_e32 v42, 0xbfb8aa3b, v74
	v_mul_f32_e32 v43, 0xbfb8aa3b, v44
	v_exp_f32_e32 v42, v42
	v_exp_f32_e32 v43, v43
	ds_read2_b32 v[46:47], v158 offset0:6 offset1:7
	ds_read2_b32 v[68:69], v158 offset0:4 offset1:5
	ds_read2_b32 v[70:71], v158 offset0:2 offset1:3
	ds_read2_b32 v[72:73], v158 offset1:1
	v_readlane_b32 s5, v254, 1
	s_mov_b32 s37, 0
	v_pk_add_f32 v[42:43], v[42:43], 1.0 op_sel_hi:[1,0]
	s_lshl_b32 s36, s36, 1
	s_waitcnt lgkmcnt(0)
	v_add_f32_e32 v32, 0, v72
	v_add_f32_e32 v32, v32, v73
	v_add_f32_e32 v32, v32, v70
	v_rcp_f32_e32 v45, v43
	s_nop 0
	v_mul_f32_e32 v43, v44, v45
	v_mul_f32_e32 v44, 0xbfb8aa3b, v79
	v_mul_f32_e32 v45, 0xbfb8aa3b, v66
	v_exp_f32_e32 v44, v44
	v_exp_f32_e32 v45, v45
	v_rcp_f32_e32 v75, v42
	s_nop 0
	v_mul_f32_e32 v42, v74, v75
	v_pk_add_f32 v[44:45], v[44:45], 1.0 op_sel_hi:[1,0]
	v_add_f32_e32 v32, v32, v71
	v_add_f32_e32 v32, v32, v68
	v_add_f32_e32 v32, v32, v69
	v_add_f32_e32 v32, v32, v46
	v_rcp_f32_e32 v67, v45
	s_nop 0
	v_mul_f32_e32 v45, v66, v67
	v_mul_f32_e32 v67, 0xbfb8aa3b, v65
	v_mul_f32_e32 v66, 0xbfb8aa3b, v87
	v_exp_f32_e32 v66, v66
	v_exp_f32_e32 v67, v67
	s_nop 0
	v_pk_add_f32 v[66:67], v[66:67], 1.0 op_sel_hi:[1,0]
	v_rcp_f32_e32 v74, v44
	s_nop 0
	v_mul_f32_e32 v44, v79, v74
	v_add_f32_e32 v32, v32, v47
	v_rcp_f32_e32 v74, v67
	s_nop 0
	v_mul_f32_e32 v65, v65, v74
	v_lshl_add_u64 v[34:35], v[34:35], 0, s[36:37]
	v_exp_f32_e32 v74, v64
	v_mul_f32_e32 v64, 0xbfb8aa3b, v126
	v_exp_f32_e32 v75, v64
	v_rcp_f32_e32 v64, v66
	s_nop 0
	v_mul_f32_e32 v64, v87, v64
	ds_read2_b32 v[76:77], v158 offset0:14 offset1:15
	ds_read2_b32 v[78:79], v158 offset0:12 offset1:13
	ds_read2_b32 v[82:83], v158 offset0:10 offset1:11
	ds_read2_b32 v[84:85], v158 offset0:8 offset1:9
	v_mov_b32_e32 v115, v33
	v_pk_add_f32 v[74:75], v[74:75], 1.0 op_sel_hi:[1,0]
	v_lshl_add_u64 v[34:35], v[34:35], 0, v[114:115]
	s_waitcnt lgkmcnt(0)
	v_add_f32_e32 v32, v32, v84
	v_add_f32_e32 v32, v32, v85
	v_add_f32_e32 v32, v32, v82
	v_rcp_f32_e32 v67, v75
	s_nop 0
	v_mul_f32_e32 v67, v126, v67
	v_add_f32_e32 v32, v32, v83
	v_rcp_f32_e32 v66, v74
	s_nop 0
	v_mul_f32_e32 v66, v121, v66
	v_mul_f32_e32 v74, 0xbfb8aa3b, v119
	v_mul_f32_e32 v75, 0xbfb8aa3b, v86
	v_exp_f32_e32 v74, v74
	v_exp_f32_e32 v75, v75
	v_add_f32_e32 v32, v32, v78
	v_add_f32_e32 v32, v32, v79
	v_add_f32_e32 v32, v32, v76
	v_pk_add_f32 v[74:75], v[74:75], 1.0 op_sel_hi:[1,0]
	v_add_f32_e32 v32, v32, v77
	s_bitset1_b32 s34, 7
	s_movk_i32 s3, 0x1800
	v_rcp_f32_e32 v87, v75
	s_nop 0
	v_mul_f32_e32 v75, v86, v87
	v_mul_f32_e32 v86, 0xbfb8aa3b, v174
	v_mul_f32_e32 v87, 0xbfb8aa3b, v62
	v_exp_f32_e32 v86, v86
	v_exp_f32_e32 v87, v87
	v_rcp_f32_e32 v121, v74
	s_nop 0
	v_mul_f32_e32 v74, v119, v121
	v_pk_add_f32 v[86:87], v[86:87], 1.0 op_sel_hi:[1,0]
	v_lshlrev_b32_e32 v119, 16, v63
	v_and_b32_e32 v121, 0xffff0000, v63
	v_lshlrev_b32_e32 v173, 16, v61
	v_and_b32_e32 v61, 0xffff0000, v61
	v_mul_f32_e32 v126, 0xbfb8aa3b, v173
	v_mul_f32_e32 v127, 0xbfb8aa3b, v61
	v_rcp_f32_e32 v63, v87
	s_nop 0
	v_mul_f32_e32 v63, v62, v63
	v_exp_f32_e32 v126, v126
	v_exp_f32_e32 v127, v127
	s_nop 0
	v_pk_add_f32 v[126:127], v[126:127], 1.0 op_sel_hi:[1,0]
	v_rcp_f32_e32 v62, v86
	s_nop 0
	v_mul_f32_e32 v62, v174, v62
	v_rcp_f32_e32 v87, v127
	s_nop 0
	v_mul_f32_e32 v87, v61, v87
	v_and_b32_e32 v127, 0xffff0000, v60
	v_mul_f32_e32 v60, 0xbfb8aa3b, v184
	v_mul_f32_e32 v61, 0xbfb8aa3b, v127
	v_exp_f32_e32 v60, v60
	v_exp_f32_e32 v61, v61
	v_rcp_f32_e32 v86, v126
	s_nop 0
	v_mul_f32_e32 v86, v173, v86
	ds_read2_b32 v[174:175], v158 offset0:22 offset1:23
	ds_read2_b32 v[176:177], v158 offset0:20 offset1:21
	ds_read2_b32 v[178:179], v158 offset0:18 offset1:19
	ds_read2_b32 v[180:181], v158 offset0:16 offset1:17
	v_pk_add_f32 v[60:61], v[60:61], 1.0 op_sel_hi:[1,0]
	s_nop 0
	s_waitcnt lgkmcnt(0)
	v_add_f32_e32 v32, v32, v180
	v_add_f32_e32 v32, v32, v181
	v_add_f32_e32 v32, v32, v178
	v_rcp_f32_e32 v126, v61
	s_nop 0
	v_mul_f32_e32 v127, v127, v126
	v_add_f32_e32 v32, v32, v179
	v_rcp_f32_e32 v126, v60
	s_nop 0
	v_mul_f32_e32 v126, v184, v126
	v_mul_f32_e32 v60, 0xbfb8aa3b, v119
	v_mul_f32_e32 v61, 0xbfb8aa3b, v121
	v_exp_f32_e32 v60, v60
	v_exp_f32_e32 v61, v61
	v_add_f32_e32 v32, v32, v176
	v_add_f32_e32 v32, v32, v177
	v_add_f32_e32 v32, v32, v174
	v_pk_add_f32 v[184:185], v[60:61], 1.0 op_sel_hi:[1,0]
	ds_read2_b32 v[186:187], v158 offset0:30 offset1:31
	ds_read2_b32 v[60:61], v158 offset0:28 offset1:29
	ds_read2_b32 v[188:189], v158 offset0:26 offset1:27
	ds_read2_b32 v[190:191], v158 offset0:24 offset1:25
	v_add_f32_e32 v32, v32, v175
	s_waitcnt lgkmcnt(0)
	v_add_f32_e32 v32, v32, v190
	v_add_f32_e32 v32, v32, v191
	v_add_f32_e32 v32, v32, v188
	v_add_f32_e32 v32, v32, v189
	v_add_f32_e32 v32, v32, v60
	v_add_f32_e32 v32, v32, v61
	v_add_f32_e32 v32, v32, v186
	v_add_f32_e32 v32, v32, v187
	ds_bpermute_b32 v194, v157, v32
	s_waitcnt lgkmcnt(0)
	v_add_f32_e32 v32, v32, v194
	ds_bpermute_b32 v194, v156, v32
	v_rcp_f32_e32 v173, v185
	s_nop 0
	v_mul_f32_e32 v185, v121, v173
	s_waitcnt lgkmcnt(0)
	v_add_f32_e32 v32, v32, v194
	v_mul_f32_e32 v32, 0x3c000000, v32
	v_pk_add_f32 v[72:73], v[72:73], v[32:33] op_sel_hi:[1,0] neg_lo:[0,1] neg_hi:[0,1]
	v_pk_add_f32 v[70:71], v[70:71], v[32:33] op_sel_hi:[1,0] neg_lo:[0,1] neg_hi:[0,1]
	v_pk_mul_f32 v[194:195], v[72:73], v[72:73]
	v_pk_mul_f32 v[196:197], v[70:71], v[70:71]
	v_pk_add_f32 v[198:199], v[68:69], v[32:33] op_sel_hi:[1,0] neg_lo:[0,1] neg_hi:[0,1]
	v_pk_add_f32 v[202:203], v[46:47], v[32:33] op_sel_hi:[1,0] neg_lo:[0,1] neg_hi:[0,1]
	v_pk_add_f32 v[84:85], v[84:85], v[32:33] op_sel_hi:[1,0] neg_lo:[0,1] neg_hi:[0,1]
	v_pk_add_f32 v[82:83], v[82:83], v[32:33] op_sel_hi:[1,0] neg_lo:[0,1] neg_hi:[0,1]
	v_pk_add_f32 v[78:79], v[78:79], v[32:33] op_sel_hi:[1,0] neg_lo:[0,1] neg_hi:[0,1]
	v_pk_add_f32 v[76:77], v[76:77], v[32:33] op_sel_hi:[1,0] neg_lo:[0,1] neg_hi:[0,1]
	v_pk_add_f32 v[180:181], v[180:181], v[32:33] op_sel_hi:[1,0] neg_lo:[0,1] neg_hi:[0,1]
	v_pk_add_f32 v[178:179], v[178:179], v[32:33] op_sel_hi:[1,0] neg_lo:[0,1] neg_hi:[0,1]
	v_pk_add_f32 v[176:177], v[176:177], v[32:33] op_sel_hi:[1,0] neg_lo:[0,1] neg_hi:[0,1]
	v_pk_add_f32 v[174:175], v[174:175], v[32:33] op_sel_hi:[1,0] neg_lo:[0,1] neg_hi:[0,1]
	v_pk_add_f32 v[190:191], v[190:191], v[32:33] op_sel_hi:[1,0] neg_lo:[0,1] neg_hi:[0,1]
	v_pk_add_f32 v[68:69], v[188:189], v[32:33] op_sel_hi:[1,0] neg_lo:[0,1] neg_hi:[0,1]
	v_pk_add_f32 v[60:61], v[60:61], v[32:33] op_sel_hi:[1,0] neg_lo:[0,1] neg_hi:[0,1]
	v_pk_add_f32 v[46:47], v[186:187], v[32:33] op_sel_hi:[1,0] neg_lo:[0,1] neg_hi:[0,1]
	v_add_f32_e32 v32, v194, v195
	v_add_f32_e32 v32, v196, v32
	v_pk_mul_f32 v[200:201], v[198:199], v[198:199]
	v_add_f32_e32 v32, v197, v32
	v_add_f32_e32 v32, v200, v32
	v_pk_mul_f32 v[206:207], v[202:203], v[202:203]
	v_add_f32_e32 v32, v201, v32
	v_add_f32_e32 v32, v206, v32
	v_pk_mul_f32 v[208:209], v[84:85], v[84:85]
	v_add_f32_e32 v32, v207, v32
	v_add_f32_e32 v32, v208, v32
	v_pk_mul_f32 v[210:211], v[82:83], v[82:83]
	v_add_f32_e32 v32, v209, v32
	v_add_f32_e32 v32, v210, v32
	v_pk_mul_f32 v[212:213], v[78:79], v[78:79]
	v_add_f32_e32 v32, v211, v32
	v_add_f32_e32 v32, v212, v32
	v_pk_mul_f32 v[214:215], v[76:77], v[76:77]
	v_add_f32_e32 v32, v213, v32
	v_add_f32_e32 v32, v214, v32
	v_pk_mul_f32 v[216:217], v[180:181], v[180:181]
	v_add_f32_e32 v32, v215, v32
	v_add_f32_e32 v32, v216, v32
	v_pk_mul_f32 v[218:219], v[178:179], v[178:179]
	v_add_f32_e32 v32, v217, v32
	v_add_f32_e32 v32, v218, v32
	v_pk_mul_f32 v[220:221], v[176:177], v[176:177]
	v_add_f32_e32 v32, v219, v32
	v_add_f32_e32 v32, v220, v32
	v_pk_mul_f32 v[222:223], v[174:175], v[174:175]
	v_add_f32_e32 v32, v221, v32
	v_add_f32_e32 v32, v222, v32
	v_pk_mul_f32 v[224:225], v[190:191], v[190:191]
	v_add_f32_e32 v32, v223, v32
	v_add_f32_e32 v32, v224, v32
	v_pk_mul_f32 v[188:189], v[68:69], v[68:69]
	v_add_f32_e32 v32, v225, v32
	v_add_f32_e32 v32, v188, v32
	v_pk_mul_f32 v[232:233], v[60:61], v[60:61]
	v_add_f32_e32 v32, v189, v32
	v_add_f32_e32 v32, v232, v32
	v_pk_mul_f32 v[186:187], v[46:47], v[46:47]
	v_add_f32_e32 v32, v233, v32
	v_add_f32_e32 v32, v186, v32
	v_add_f32_e32 v32, v187, v32
	ds_bpermute_b32 v186, v157, v32
	s_mov_b32 s0, 0xf800000
	s_waitcnt lgkmcnt(0)
	v_add_f32_e32 v32, v32, v186
	ds_bpermute_b32 v173, v156, v32
	s_waitcnt lgkmcnt(0)
	v_add_f32_e32 v32, v32, v173
	v_mov_b32_e32 v173, 0x358637bd
	v_fmac_f32_e32 v173, 0x3c000000, v32
	v_mul_f32_e32 v32, 0x4f800000, v173
	v_cmp_gt_f32_e64 s[0:1], s0, v173
	s_nop 1
	v_cndmask_b32_e64 v32, v173, v32, s[0:1]
	v_sqrt_f32_e32 v173, v32
	s_nop 0
	v_add_u32_e32 v187, -1, v173
	v_fma_f32 v188, -v187, v173, v32
	v_cmp_ge_f32_e64 s[4:5], 0, v188
	v_add_u32_e32 v188, 1, v173
	v_rcp_f32_e32 v121, v184
	s_nop 0
	v_mul_f32_e32 v184, v119, v121
	v_cndmask_b32_e64 v187, v173, v187, s[4:5]
	v_fma_f32 v173, -v188, v173, v32
	v_cmp_lt_f32_e64 s[4:5], 0, v173
	s_nop 1
	v_cndmask_b32_e64 v173, v187, v188, s[4:5]
	v_mul_f32_e32 v187, 0x37800000, v173
	v_cndmask_b32_e64 v173, v173, v187, s[0:1]
	v_mov_b32_e32 v187, 0x260
	v_cmp_class_f32_e64 s[0:1], v32, v187
	s_nop 1
	v_cndmask_b32_e64 v32, v173, v32, s[0:1]
	v_rcp_f32_e32 v32, v32
	s_nop 0
	v_pk_mul_f32 v[72:73], v[72:73], v[32:33] op_sel_hi:[1,0]
	v_mov_b32_e32 v119, v33
	s_waitcnt vmcnt(4)
	v_pk_mul_f32 v[28:29], v[28:29], v[72:73]
	v_mov_b32_e32 v121, v33
	v_pk_mul_f32 v[28:29], v[40:41], v[28:29]
	v_pk_mul_f32 v[40:41], v[70:71], v[32:33] op_sel_hi:[1,0]
	s_nop 0
	v_pk_mul_f32 v[30:31], v[30:31], v[40:41]
	v_lshlrev_b32_e32 v40, 16, v50
	v_pk_mul_f32 v[30:31], v[38:39], v[30:31]
	v_pk_mul_f32 v[38:39], v[198:199], v[32:33] op_sel_hi:[1,0]
	v_and_b32_e32 v41, 0xffff0000, v50
	v_pk_mul_f32 v[24:25], v[24:25], v[38:39]
	v_pk_fma_f32 v[40:41], v[124:125], v[146:147], v[40:41] op_sel_hi:[0,1,1]
	v_pk_mul_f32 v[36:37], v[36:37], v[24:25]
	v_pk_mul_f32 v[24:25], v[202:203], v[32:33] op_sel_hi:[1,0]
	s_nop 0
	v_pk_mul_f32 v[24:25], v[26:27], v[24:25]
	v_cvt_pk_bf16_f32 v26, v36, v37
	v_pk_mul_f32 v[38:39], v[42:43], v[24:25]
	v_cvt_pk_bf16_f32 v24, v28, v29
	v_cvt_pk_bf16_f32 v25, v30, v31
	v_cvt_pk_bf16_f32 v27, v38, v39
	global_store_dwordx4 v[34:35], v[24:27], off
	v_mov_b32_e32 v28, 0x1800
	v_and_b32_e32 v29, 0xffff0000, v52
	v_pk_mul_f32 v[24:25], v[84:85], v[32:33] op_sel_hi:[1,0]
	v_lshlrev_b32_e32 v30, 16, v53
	v_pk_mul_f32 v[20:21], v[20:21], v[24:25]
	v_pk_mul_f32 v[24:25], v[82:83], v[32:33] op_sel_hi:[1,0]
	v_pk_mul_f32 v[20:21], v[66:67], v[20:21]
	v_pk_mul_f32 v[22:23], v[22:23], v[24:25]
	v_pk_mul_f32 v[24:25], v[78:79], v[32:33] op_sel_hi:[1,0]
	v_pk_mul_f32 v[22:23], v[64:65], v[22:23]
	v_pk_mul_f32 v[16:17], v[16:17], v[24:25]
	v_lshl_add_u64 v[82:83], s[34:35], 0, v[112:113]
	v_pk_mul_f32 v[24:25], v[44:45], v[16:17]
	v_pk_mul_f32 v[16:17], v[76:77], v[32:33] op_sel_hi:[1,0]
	v_and_b32_e32 v31, 0xffff0000, v53
	v_pk_mul_f32 v[16:17], v[18:19], v[16:17]
	v_cvt_pk_bf16_f32 v18, v24, v25
	v_pk_mul_f32 v[26:27], v[74:75], v[16:17]
	v_cvt_pk_bf16_f32 v16, v20, v21
	v_cvt_pk_bf16_f32 v17, v22, v23
	v_cvt_pk_bf16_f32 v19, v26, v27
	global_store_dwordx4 v[34:35], v[16:19], off offset:16
	v_lshlrev_b32_e32 v20, 16, v56
	v_and_b32_e32 v21, 0xffff0000, v56
	v_pk_mul_f32 v[16:17], v[180:181], v[32:33] op_sel_hi:[1,0]
	v_mov_b64_e32 v[24:25], s[26:27]
	s_waitcnt vmcnt(2)
	v_pk_mul_f32 v[12:13], v[12:13], v[16:17]
	v_pk_mul_f32 v[16:17], v[178:179], v[32:33] op_sel_hi:[1,0]
	v_pk_mul_f32 v[12:13], v[126:127], v[12:13]
	v_pk_mul_f32 v[14:15], v[14:15], v[16:17]
	v_pk_mul_f32 v[16:17], v[176:177], v[32:33] op_sel_hi:[1,0]
	v_pk_mul_f32 v[14:15], v[86:87], v[14:15]
	v_pk_mul_f32 v[8:9], v[8:9], v[16:17]
	v_lshlrev_b32_e32 v36, 16, v48
	v_pk_mul_f32 v[16:17], v[62:63], v[8:9]
	v_pk_mul_f32 v[8:9], v[174:175], v[32:33] op_sel_hi:[1,0]
	v_and_b32_e32 v37, 0xffff0000, v48
	v_pk_mul_f32 v[8:9], v[10:11], v[8:9]
	v_mul_f32_e32 v10, 0xbfb8aa3b, v20
	v_mul_f32_e32 v11, 0xbfb8aa3b, v21
	v_exp_f32_e32 v10, v10
	v_exp_f32_e32 v11, v11
	v_pk_mul_f32 v[18:19], v[184:185], v[8:9]
	v_cvt_pk_bf16_f32 v8, v12, v13
	v_cvt_pk_bf16_f32 v9, v14, v15
	v_pk_add_f32 v[12:13], v[10:11], 1.0 op_sel_hi:[1,0]
	v_cvt_pk_bf16_f32 v10, v16, v17
	v_cvt_pk_bf16_f32 v11, v18, v19
	global_store_dwordx4 v[34:35], v[8:11], off offset:32
	v_and_b32_e32 v16, 0xffff0000, v57
	v_lshlrev_b32_e32 v38, 16, v49
	v_rcp_f32_e32 v9, v13
	s_nop 0
	v_mul_f32_e32 v9, v21, v9
	v_lshlrev_b32_e32 v15, 16, v57
	v_mul_f32_e32 v10, 0xbfb8aa3b, v15
	v_mul_f32_e32 v11, 0xbfb8aa3b, v16
	v_exp_f32_e32 v10, v10
	v_exp_f32_e32 v11, v11
	v_rcp_f32_e32 v8, v12
	s_nop 0
	v_mul_f32_e32 v8, v20, v8
	v_pk_mul_f32 v[12:13], v[190:191], v[32:33] op_sel_hi:[1,0]
	v_pk_add_f32 v[10:11], v[10:11], 1.0 op_sel_hi:[1,0]
	v_pk_mul_f32 v[4:5], v[4:5], v[12:13]
	v_pk_mul_f32 v[4:5], v[8:9], v[4:5]
	v_lshl_add_u64 v[20:21], s[34:35], 0, v[116:117]
	v_mad_u64_u32 v[22:23], s[4:5], v20, s3, v[24:25]
	v_rcp_f32_e32 v9, v11
	s_nop 0
	v_mul_f32_e32 v9, v16, v9
	v_lshlrev_b32_e32 v16, 16, v58
	v_and_b32_e32 v17, 0xffff0000, v58
	v_mul_f32_e32 v12, 0xbfb8aa3b, v16
	v_mul_f32_e32 v13, 0xbfb8aa3b, v17
	v_exp_f32_e32 v12, v12
	v_exp_f32_e32 v13, v13
	v_rcp_f32_e32 v8, v10
	s_nop 0
	v_mul_f32_e32 v8, v15, v8
	v_mad_u32_u24 v23, v21, s3, v23
	v_pk_add_f32 v[10:11], v[12:13], 1.0 op_sel_hi:[1,0]
	v_pk_mul_f32 v[12:13], v[68:69], v[32:33] op_sel_hi:[1,0]
	v_pk_mul_f32 v[6:7], v[6:7], v[12:13]
	v_and_b32_e32 v39, 0xffff0000, v49
	v_pk_mul_f32 v[6:7], v[8:9], v[6:7]
	v_rcp_f32_e32 v9, v11
	s_nop 0
	v_mul_f32_e32 v9, v17, v9
	v_lshlrev_b32_e32 v15, 16, v59
	v_and_b32_e32 v17, 0xffff0000, v59
	v_mul_f32_e32 v12, 0xbfb8aa3b, v15
	v_mul_f32_e32 v13, 0xbfb8aa3b, v17
	v_exp_f32_e32 v12, v12
	v_exp_f32_e32 v13, v13
	v_rcp_f32_e32 v8, v10
	s_nop 0
	v_mul_f32_e32 v8, v16, v8
	v_pk_fma_f32 v[30:31], v[124:125], v[136:137], v[30:31] op_sel_hi:[0,1,1]
	v_pk_add_f32 v[10:11], v[12:13], 1.0 op_sel_hi:[1,0]
	v_pk_mul_f32 v[12:13], v[60:61], v[32:33] op_sel_hi:[1,0]
	v_pk_mul_f32 v[0:1], v[0:1], v[12:13]
	v_pk_fma_f32 v[36:37], v[124:125], v[142:143], v[36:37] op_sel_hi:[0,1,1]
	v_pk_mul_f32 v[8:9], v[8:9], v[0:1]
	v_rcp_f32_e32 v1, v11
	s_nop 0
	v_mul_f32_e32 v1, v17, v1
	v_rcp_f32_e32 v0, v10
	s_nop 0
	v_mul_f32_e32 v0, v15, v0
	v_pk_mul_f32 v[10:11], v[46:47], v[32:33] op_sel_hi:[1,0]
	v_or_b32_e32 v16, s34, v205
	v_pk_mul_f32 v[2:3], v[2:3], v[10:11]
	v_mad_u64_u32 v[16:17], s[0:1], v16, s3, v[24:25]
	v_pk_mul_f32 v[10:11], v[0:1], v[2:3]
	v_cvt_pk_bf16_f32 v0, v4, v5
	v_cvt_pk_bf16_f32 v1, v6, v7
	v_cvt_pk_bf16_f32 v2, v8, v9
	v_cvt_pk_bf16_f32 v3, v10, v11
	global_store_dwordx4 v[34:35], v[0:3], off offset:48
	v_or_b32_e32 v8, s34, v154
	v_lshl_add_u64 v[10:11], s[34:35], 0, v[122:123]
	v_or_b32_e32 v0, s34, v152
	v_or_b32_e32 v2, s34, v153
	v_mad_u64_u32 v[0:1], s[0:1], v0, s3, v[24:25]
	v_mad_u64_u32 v[2:3], s[0:1], v2, s3, v[24:25]
	v_mad_u64_u32 v[8:9], s[0:1], v8, s3, v[24:25]
	v_mad_u64_u32 v[12:13], s[0:1], v10, s3, v[24:25]
	v_mad_u32_u24 v1, s35, v28, v1
	v_mad_u32_u24 v3, s35, v28, v3
	v_mad_u32_u24 v9, s35, v28, v9
	v_mad_u32_u24 v13, v11, s3, v13
	v_lshl_add_u64 v[0:1], v[0:1], 0, s[36:37]
	v_lshl_add_u64 v[2:3], v[2:3], 0, s[36:37]
	v_lshl_add_u64 v[8:9], v[8:9], 0, s[36:37]
	v_lshl_add_u64 v[10:11], v[12:13], 0, s[36:37]
	v_mad_u32_u24 v17, s35, v28, v17
	s_lshl_b32 s0, s31, 1
	s_mov_b32 s1, s37
	s_waitcnt lgkmcnt(0)
	s_barrier
	v_lshl_add_u64 v[0:1], v[0:1], 0, v[118:119]
	v_lshl_add_u64 v[4:5], v[2:3], 0, v[118:119]
	v_lshl_add_u64 v[8:9], v[8:9], 0, v[118:119]
	v_lshl_add_u64 v[12:13], v[10:11], 0, v[118:119]
	v_lshl_add_u64 v[16:17], v[16:17], 0, s[0:1]
	v_lshl_add_u64 v[20:21], v[22:23], 0, s[0:1]
	global_load_dwordx4 v[0:3], v[0:1], off offset:1024
	s_nop 0
	global_load_dwordx4 v[4:7], v[4:5], off offset:1024
	s_nop 0
	global_load_dwordx4 v[8:11], v[8:9], off offset:1024
	s_nop 0
	global_load_dwordx4 v[12:15], v[12:13], off offset:1024
	v_lshl_add_u64 v[16:17], v[16:17], 0, v[120:121]
	v_lshl_add_u64 v[20:21], v[20:21], 0, v[120:121]
	global_load_dwordx4 v[16:19], v[16:17], off offset:512
	s_add_u32 s4, s34, s41
	global_load_dwordx4 v[20:23], v[20:21], off offset:512
	v_or_b32_e32 v26, s4, v228
	s_addc_u32 s6, s35, 0
	v_mad_u64_u32 v[26:27], s[4:5], v26, s3, v[24:25]
	v_mad_u32_u24 v27, s6, v28, v27
	v_lshl_add_u64 v[26:27], v[26:27], 0, s[0:1]
	v_lshlrev_b32_e32 v32, 1, v155
	v_lshl_add_u64 v[26:27], v[26:27], 0, v[32:33]
	global_load_dwordx4 v[64:67], v[26:27], off
	global_load_dwordx4 v[68:71], v[26:27], off offset:32
	global_load_dwordx4 v[72:75], v[26:27], off offset:64
	global_load_dwordx4 v[76:79], v[26:27], off offset:96
	v_mad_u64_u32 v[24:25], s[0:1], v82, s3, v[24:25]
	v_mad_u32_u24 v25, v83, s3, v25
	v_lshl_add_u64 v[24:25], v[24:25], 0, s[36:37]
	v_lshl_add_u64 v[24:25], v[24:25], 0, v[114:115]
	v_lshlrev_b32_e32 v28, 16, v52
	v_lshlrev_b32_e32 v32, 16, v54
	v_and_b32_e32 v33, 0xffff0000, v54
	v_lshlrev_b32_e32 v34, 16, v55
	v_and_b32_e32 v35, 0xffff0000, v55
	v_lshlrev_b32_e32 v26, 16, v51
	v_and_b32_e32 v27, 0xffff0000, v51
	global_load_dwordx4 v[48:51], v[24:25], off offset:2096
	global_load_dwordx4 v[52:55], v[24:25], off offset:2080
	global_load_dwordx4 v[56:59], v[24:25], off offset:2064
	global_load_dwordx4 v[60:63], v[24:25], off offset:2048
	v_pk_fma_f32 v[28:29], v[124:125], v[134:135], v[28:29] op_sel_hi:[0,1,1]
	v_pk_fma_f32 v[32:33], v[124:125], v[138:139], v[32:33] op_sel_hi:[0,1,1]
	v_pk_fma_f32 v[34:35], v[124:125], v[140:141], v[34:35] op_sel_hi:[0,1,1]
	v_pk_fma_f32 v[38:39], v[124:125], v[144:145], v[38:39] op_sel_hi:[0,1,1]
	v_pk_fma_f32 v[42:43], v[124:125], v[148:149], v[26:27] op_sel_hi:[0,1,1]
	v_cvt_pk_bf16_f32 v24, v28, v29
	v_cvt_pk_bf16_f32 v25, v30, v31
	v_cvt_pk_bf16_f32 v26, v32, v33
	v_cvt_pk_bf16_f32 v27, v34, v35
	v_add_u32_e32 v28, v163, v168
	ds_write_b128 v28, v[24:27] offset:51200
	v_cvt_pk_bf16_f32 v24, v36, v37
	v_cvt_pk_bf16_f32 v25, v38, v39
	v_cvt_pk_bf16_f32 v26, v40, v41
	v_cvt_pk_bf16_f32 v27, v42, v43
	v_add_u32_e32 v29, v163, v169
	ds_write_b128 v29, v[24:27] offset:51200
	s_waitcnt vmcnt(13)
	ds_write_b128 v164, v[0:3] offset:18432
	s_waitcnt vmcnt(12)
	ds_write_b128 v165, v[4:7] offset:18432
	s_waitcnt vmcnt(11)
	ds_write_b128 v164, v[8:11] offset:22528
	s_waitcnt vmcnt(10)
	ds_write_b128 v166, v[12:15] offset:18432
	s_waitcnt vmcnt(9)
	ds_write_b128 v28, v[16:19]
	v_add_u32_e32 v0, v163, v171
	v_add_u32_e32 v36, v167, v170
	s_mov_b32 s3, 0x5040100
	s_waitcnt vmcnt(8)
	ds_write_b128 v0, v[20:23]
	s_waitcnt lgkmcnt(0)
	s_barrier
	ds_read_b128 v[0:3], v36 offset:51200
	ds_read_b128 v[16:19], v36 offset:51232
	s_waitcnt vmcnt(7) lgkmcnt(1)
	v_mfma_f32_32x32x16_bf16 v[0:15], v[0:3], v[64:67], 0
	s_waitcnt vmcnt(6) lgkmcnt(0)
	v_mfma_f32_32x32x16_bf16 v[0:15], v[16:19], v[68:71], v[0:15]
	ds_read_b128 v[16:19], v36 offset:51264
	ds_read_b128 v[20:23], v36 offset:51296
	s_waitcnt vmcnt(5) lgkmcnt(1)
	v_mfma_f32_32x32x16_bf16 v[0:15], v[16:19], v[72:75], v[0:15]
	ds_read_b128 v[16:19], v36 offset:55808
	ds_read_b128 v[32:35], v36 offset:55840
	s_waitcnt vmcnt(4) lgkmcnt(2)
	v_mfma_f32_32x32x16_bf16 v[0:15], v[20:23], v[76:79], v[0:15]
	s_waitcnt lgkmcnt(1)
	v_mfma_f32_32x32x16_bf16 v[16:31], v[16:19], v[64:67], 0
	s_nop 9
	v_mul_f32_e64 v14, v132, v14
	v_mul_f32_e64 v15, v133, v15
	v_mul_f32_e64 v12, v130, v12
	v_mul_f32_e64 v13, v131, v13
	v_mul_f32_e64 v10, v128, v10
	v_mul_f32_e64 v11, v129, v11
	v_pk_mul_f32 v[8:9], v[110:111], v[8:9]
	v_pk_mul_f32 v[6:7], v[108:109], v[6:7]
	v_pk_mul_f32 v[4:5], v[106:107], v[4:5]
	v_pk_mul_f32 v[2:3], v[104:105], v[2:3]
	s_waitcnt lgkmcnt(0)
	v_mfma_f32_32x32x16_bf16 v[16:31], v[32:35], v[68:71], v[16:31]
	ds_read_b128 v[32:35], v36 offset:55872
	ds_read_b128 v[36:39], v36 offset:55904
	v_mul_f32_e64 v0, v102, v0
	v_mul_f32_e64 v1, v103, v1
	s_waitcnt lgkmcnt(1)
	v_mfma_f32_32x32x16_bf16 v[16:31], v[32:35], v[72:75], v[16:31]
	s_waitcnt lgkmcnt(0)
	v_mfma_f32_32x32x16_bf16 v[16:31], v[36:39], v[76:79], v[16:31]
	s_nop 11
	v_pk_mul_f32 v[30:31], v[132:133], v[30:31]
	v_pk_mul_f32 v[28:29], v[130:131], v[28:29]
	v_pk_mul_f32 v[26:27], v[128:129], v[26:27]
	v_pk_mul_f32 v[24:25], v[110:111], v[24:25]
	v_pk_mul_f32 v[22:23], v[108:109], v[22:23]
	v_pk_mul_f32 v[20:21], v[106:107], v[20:21]
	v_pk_mul_f32 v[18:19], v[104:105], v[18:19]
	v_pk_mul_f32 v[16:17], v[102:103], v[16:17]
.LBB0_588:
	v_add_u32_e32 v113, v161, v159
	v_sub_u32_e32 v115, v159, v89
	v_sub_u32_e32 v124, v159, v88
	v_sub_u32_e32 v138, v159, v91
	v_sub_u32_e32 v139, v159, v90
	v_sub_u32_e32 v140, v159, v93
	v_sub_u32_e32 v141, v159, v92
	v_sub_u32_e32 v142, v159, v95
	v_sub_u32_e32 v143, v159, v94
	v_cvt_f32_u32_e32 v39, v113
	v_cvt_f32_u32_e32 v40, v124
	v_cvt_f32_u32_e32 v41, v115
	v_cvt_f32_u32_e32 v42, v139
	v_cvt_f32_u32_e32 v43, v138
	v_cvt_f32_u32_e32 v44, v141
	v_cvt_f32_u32_e32 v45, v140
	v_cvt_f32_u32_e32 v46, v143
	v_cvt_f32_u32_e32 v47, v142
	ds_read_b128 v[32:35], v162
	ds_read_b128 v[84:87], v162 offset:32
	ds_read_b128 v[102:105], v162 offset:64
	ds_read_b128 v[106:109], v162 offset:96
	v_add_u32_e32 v36, 0xffffdc00, v160
	v_add_u32_e32 v37, 0xfffffc00, v160
	v_add_u32_e32 v38, 0xffffe000, v160
	ds_read_b64_tr_b16 v[120:121], v36
	ds_read_b64_tr_b16 v[122:123], v36 offset:512
	ds_read_b64_tr_b16 v[116:117], v37
	ds_read_b64_tr_b16 v[118:119], v37 offset:512
	s_waitcnt lgkmcnt(0)
	ds_read_b64_tr_b16 v[130:131], v38
	ds_read_b64_tr_b16 v[132:133], v38 offset:512
	ds_read_b64_tr_b16 v[126:127], v160
	ds_read_b64_tr_b16 v[128:129], v160 offset:512
	s_waitcnt lgkmcnt(0)
	v_mul_f32_e32 v154, v151, v39
	v_mul_f32_e32 v155, v151, v40
	v_mul_f32_e32 v163, v151, v41
	v_mul_f32_e32 v164, v151, v42
	v_mul_f32_e32 v165, v151, v43
	v_mul_f32_e32 v166, v151, v44
	v_mul_f32_e32 v167, v151, v45
	v_mul_f32_e32 v168, v151, v46
	v_mul_f32_e32 v169, v151, v47
	s_waitcnt lgkmcnt(3)
	v_mfma_f32_32x32x16_bf16 v[32:47], v[32:35], v[64:67], 0
	v_add_u32_e32 v152, -1, v113
	v_sub_u32_e32 v144, v159, v97
	v_sub_u32_e32 v145, v159, v96
	v_sub_u32_e32 v146, v159, v99
	v_sub_u32_e32 v147, v159, v98
	v_sub_u32_e32 v148, v159, v101
	v_sub_u32_e32 v149, v159, v100
	s_waitcnt lgkmcnt(2)
	v_mfma_f32_32x32x16_bf16 v[32:47], v[84:87], v[68:71], v[32:47]
	v_cvt_f32_u32_e32 v153, v152
	v_cvt_f32_u32_e32 v110, v145
	v_cvt_f32_u32_e32 v111, v144
	v_cvt_f32_u32_e32 v134, v147
	v_cvt_f32_u32_e32 v135, v146
	v_cvt_f32_u32_e32 v136, v149
	v_cvt_f32_u32_e32 v137, v148
	s_waitcnt lgkmcnt(1)
	v_mfma_f32_32x32x16_bf16 v[32:47], v[102:105], v[72:75], v[32:47]
	v_mul_f32_e32 v153, v151, v153
	v_mul_f32_e32 v170, v151, v110
	v_mul_f32_e32 v171, v151, v111
	v_mul_f32_e32 v173, v151, v134
	v_mul_f32_e32 v174, v151, v135
	v_mul_f32_e32 v136, v151, v136
	v_mul_f32_e32 v137, v151, v137
	s_waitcnt lgkmcnt(0)
	v_mfma_f32_32x32x16_bf16 v[32:47], v[106:109], v[76:79], v[32:47]
	v_exp_f32_e32 v154, v154
	v_exp_f32_e32 v110, v155
	v_exp_f32_e32 v111, v163
	v_exp_f32_e32 v84, v164
	v_exp_f32_e32 v85, v165
	v_exp_f32_e32 v86, v166
	v_exp_f32_e32 v87, v167
	v_exp_f32_e32 v153, v153
	v_exp_f32_e32 v134, v168
	v_exp_f32_e32 v135, v169
	v_exp_f32_e32 v102, v170
	v_exp_f32_e32 v103, v171
	v_exp_f32_e32 v104, v173
	v_exp_f32_e32 v105, v174
	v_exp_f32_e32 v136, v136
	v_exp_f32_e32 v137, v137
	v_mul_f32_e32 v106, v154, v32
	v_mul_f32_e32 v107, v153, v33
	v_cmp_lt_i32_e32 vcc, -1, v152
	v_pk_mul_f32 v[32:33], v[110:111], v[34:35]
	v_pk_mul_f32 v[34:35], v[84:85], v[36:37]
	v_pk_mul_f32 v[36:37], v[86:87], v[38:39]
	v_pk_mul_f32 v[38:39], v[134:135], v[40:41]
	v_pk_mul_f32 v[40:41], v[102:103], v[42:43]
	v_pk_mul_f32 v[42:43], v[104:105], v[44:45]
	v_pk_mul_f32 v[44:45], v[136:137], v[46:47]
	v_cmp_lt_i32_e64 s[0:1], -1, v113
	v_cndmask_b32_e32 v47, 0, v107, vcc
	v_cvt_pk_bf16_f32 v33, v32, v33
	v_cmp_lt_i32_e32 vcc, -1, v124
	v_cvt_pk_bf16_f32 v34, v34, v35
	v_cvt_pk_bf16_f32 v35, v36, v37
	v_cndmask_b32_e64 v46, 0, v106, s[0:1]
	v_cmp_lt_i32_e64 s[0:1], -1, v139
	v_cmp_lt_i32_e64 s[4:5], -1, v141
	v_cvt_pk_bf16_f32 v36, v38, v39
	v_cvt_pk_bf16_f32 v37, v40, v41
	v_cvt_pk_bf16_f32 v39, v44, v45
	v_lshrrev_b32_e32 v40, 16, v34
	v_cmp_lt_i32_e64 s[14:15], -1, v138
	v_lshrrev_b32_e32 v41, 16, v35
	v_cmp_lt_i32_e64 s[16:17], -1, v140
	v_cndmask_b32_e32 v45, 0, v33, vcc
	v_lshrrev_b32_e32 v33, 16, v33
	v_cmp_lt_i32_e32 vcc, -1, v115
	v_cndmask_b32_e64 v34, 0, v34, s[0:1]
	v_cndmask_b32_e64 v35, 0, v35, s[4:5]
	v_cndmask_b32_e32 v33, 0, v33, vcc
	v_cndmask_b32_e64 v40, 0, v40, s[14:15]
	v_cndmask_b32_e64 v41, 0, v41, s[16:17]
	v_cvt_pk_bf16_f32 v32, v46, v47
	v_perm_b32 v33, v33, v45, s3
	v_perm_b32 v34, v40, v34, s3
	v_perm_b32 v35, v41, v35, s3
	v_cmp_lt_i32_e64 s[6:7], -1, v143
	v_cvt_pk_bf16_f32 v38, v42, v43
	v_mfma_f32_32x32x16_bf16 v[0:15], v[120:123], v[32:35], v[0:15]
	v_cmp_lt_i32_e64 s[8:9], -1, v145
	v_cmp_lt_i32_e64 s[10:11], -1, v147
	v_cmp_lt_i32_e64 s[12:13], -1, v149
	v_lshrrev_b32_e32 v42, 16, v37
	v_cmp_lt_i32_e64 s[18:19], -1, v144
	v_lshrrev_b32_e32 v43, 16, v38
	v_cmp_lt_i32_e64 s[20:21], -1, v146
	v_mfma_f32_32x32x16_bf16 v[16:31], v[116:119], v[32:35], v[16:31]
	v_lshrrev_b32_e32 v44, 16, v39
	v_cmp_lt_i32_e64 s[22:23], -1, v148
	v_cndmask_b32_e64 v40, 0, v36, s[6:7]
	v_lshrrev_b32_e32 v36, 16, v36
	v_cmp_lt_i32_e32 vcc, -1, v142
	v_cndmask_b32_e64 v37, 0, v37, s[8:9]
	v_cndmask_b32_e64 v38, 0, v38, s[10:11]
	v_cndmask_b32_e64 v39, 0, v39, s[12:13]
	v_cndmask_b32_e32 v36, 0, v36, vcc
	v_cndmask_b32_e64 v33, 0, v42, s[18:19]
	v_cndmask_b32_e64 v34, 0, v43, s[20:21]
	v_cndmask_b32_e64 v35, 0, v44, s[22:23]
	v_perm_b32 v32, v36, v40, s3
	v_perm_b32 v33, v33, v37, s3
	v_perm_b32 v34, v34, v38, s3
	v_perm_b32 v35, v35, v39, s3
	s_add_i32 s2, s2, -1
	v_subrev_u32_e32 v159, 32, v159
	v_mfma_f32_32x32x16_bf16 v[0:15], v[130:133], v[32:35], v[0:15]
	v_add_u32_e32 v162, 0x1200, v162
	s_cmp_lg_u32 s2, 0
	v_add_u32_e32 v160, 0x800, v160
	v_mfma_f32_32x32x16_bf16 v[16:31], v[126:129], v[32:35], v[16:31]
	s_cbranch_scc1 .LBB0_588
	v_lshlrev_b64 v[32:33], 12, v[82:83]
	v_readlane_b32 s4, v254, 0
	v_lshlrev_b32_e32 v36, 11, v82
	v_and_b32_e32 v32, 0xfff00000, v32
	v_readlane_b32 s6, v254, 2
	v_readlane_b32 s7, v254, 3
	s_waitcnt vmcnt(0)
	v_lshlrev_b32_e32 v40, 16, v62
	v_and_b32_e32 v38, 0xffff0000, v62
	v_lshl_add_u64 v[34:35], s[6:7], 0, v[32:33]
	v_and_b32_e32 v32, 0x7f800, v36
	v_mul_f32_e32 v36, 0xbfb8aa3b, v40
	v_mul_f32_e32 v37, 0xbfb8aa3b, v38
	v_exp_f32_e32 v36, v36
	v_exp_f32_e32 v37, v37
	v_mov_b32_e32 v33, 0
	v_lshl_add_u64 v[34:35], v[34:35], 0, v[32:33]
	v_lshlrev_b32_e32 v45, 16, v61
	v_pk_add_f32 v[36:37], v[36:37], 1.0 op_sel_hi:[1,0]
	v_and_b32_e32 v46, 0xffff0000, v61
	v_lshlrev_b32_e32 v66, 16, v63
	v_and_b32_e32 v44, 0xffff0000, v63
	v_lshlrev_b32_e32 v71, 16, v58
	v_rcp_f32_e32 v32, v37
	s_nop 0
	v_mul_f32_e32 v37, v38, v32
	v_mul_f32_e32 v38, 0xbfb8aa3b, v45
	v_mul_f32_e32 v39, 0xbfb8aa3b, v46
	v_exp_f32_e32 v38, v38
	v_exp_f32_e32 v39, v39
	s_nop 0
	v_pk_add_f32 v[38:39], v[38:39], 1.0 op_sel_hi:[1,0]
	v_rcp_f32_e32 v32, v36
	s_nop 0
	v_mul_f32_e32 v36, v40, v32
	v_and_b32_e32 v58, 0xffff0000, v58
	v_rcp_f32_e32 v32, v39
	s_nop 0
	v_mul_f32_e32 v39, v46, v32
	v_lshlrev_b32_e32 v78, 16, v59
	v_lshlrev_b32_e32 v42, 16, v60
	v_and_b32_e32 v43, 0xffff0000, v60
	v_mul_f32_e32 v40, 0xbfb8aa3b, v42
	v_mul_f32_e32 v41, 0xbfb8aa3b, v43
	v_exp_f32_e32 v40, v40
	v_exp_f32_e32 v41, v41
	v_rcp_f32_e32 v32, v38
	s_nop 0
	v_mul_f32_e32 v38, v45, v32
	v_and_b32_e32 v76, 0xffff0000, v59
	v_lshlrev_b32_e32 v77, 16, v57
	v_pk_add_f32 v[40:41], v[40:41], 1.0 op_sel_hi:[1,0]
	v_and_b32_e32 v57, 0xffff0000, v57
	v_div_scale_f32 v67, s[0:1], v41, v41, v43
	v_rcp_f32_e32 v68, v67
	s_waitcnt lgkmcnt(0)
	s_barrier
	v_rcp_f32_e32 v45, v41
	s_nop 0
	v_mul_f32_e32 v41, v43, v45
	ds_write2_b32 v172, v0, v1 offset1:1
	ds_write2_b32 v172, v2, v3 offset0:2 offset1:3
	ds_write2_b32 v172, v4, v5 offset0:8 offset1:9
	ds_write2_b32 v172, v6, v7 offset0:10 offset1:11
	ds_write2_b32 v172, v8, v9 offset0:16 offset1:17
	ds_write2_b32 v172, v10, v11 offset0:18 offset1:19
	ds_write2_b32 v172, v12, v13 offset0:24 offset1:25
	ds_write2_b32 v172, v14, v15 offset0:26 offset1:27
	ds_write2_b32 v172, v16, v17 offset0:40 offset1:41
	ds_write2_b32 v172, v18, v19 offset0:42 offset1:43
	ds_write2_b32 v172, v20, v21 offset0:48 offset1:49
	ds_write2_b32 v172, v22, v23 offset0:50 offset1:51
	ds_write2_b32 v172, v24, v25 offset0:56 offset1:57
	ds_write2_b32 v172, v26, v27 offset0:58 offset1:59
	ds_write2_b32 v172, v28, v29 offset0:64 offset1:65
	ds_write2_b32 v172, v30, v31 offset0:66 offset1:67
	v_rcp_f32_e32 v43, v40
	s_nop 0
	v_mul_f32_e32 v40, v42, v43
	v_mul_f32_e32 v42, 0xbfb8aa3b, v66
	v_mul_f32_e32 v43, 0xbfb8aa3b, v44
	v_exp_f32_e32 v42, v42
	v_exp_f32_e32 v43, v43
	s_waitcnt lgkmcnt(0)
	s_barrier
	v_pk_add_f32 v[42:43], v[42:43], 1.0 op_sel_hi:[1,0]
	v_lshlrev_b32_e32 v79, 16, v56
	global_load_dwordx4 v[16:19], v[80:81], off offset:48
	global_load_dwordx4 v[20:23], v[80:81], off offset:32
	global_load_dwordx4 v[24:27], v[80:81], off offset:16
	global_load_dwordx4 v[28:31], v[80:81], off
	global_load_dwordx4 v[0:3], v[80:81], off offset:112
	global_load_dwordx4 v[4:7], v[80:81], off offset:96
	global_load_dwordx4 v[8:11], v[80:81], off offset:80
	global_load_dwordx4 v[12:15], v[80:81], off offset:64
	v_and_b32_e32 v80, 0xffff0000, v56
	v_mul_f32_e32 v56, 0xbfb8aa3b, v79
	v_rcp_f32_e32 v45, v43
	s_nop 0
	v_mul_f32_e32 v43, v44, v45
	v_mul_f32_e32 v44, 0xbfb8aa3b, v71
	v_mul_f32_e32 v45, 0xbfb8aa3b, v58
	v_exp_f32_e32 v44, v44
	v_exp_f32_e32 v45, v45
	v_rcp_f32_e32 v67, v42
	s_nop 0
	v_mul_f32_e32 v42, v66, v67
	v_pk_add_f32 v[44:45], v[44:45], 1.0 op_sel_hi:[1,0]
	v_lshlrev_b32_e32 v83, 16, v54
	v_and_b32_e32 v54, 0xffff0000, v54
	v_lshlrev_b32_e32 v113, 16, v55
	v_and_b32_e32 v124, 0xffff0000, v55
	v_rcp_f32_e32 v59, v45
	s_nop 0
	v_mul_f32_e32 v45, v58, v59
	v_mul_f32_e32 v59, 0xbfb8aa3b, v57
	v_mul_f32_e32 v58, 0xbfb8aa3b, v77
	v_exp_f32_e32 v58, v58
	v_exp_f32_e32 v59, v59
	s_nop 0
	v_pk_add_f32 v[58:59], v[58:59], 1.0 op_sel_hi:[1,0]
	v_rcp_f32_e32 v66, v44
	s_nop 0
	v_mul_f32_e32 v44, v71, v66
	v_lshlrev_b32_e32 v88, 16, v53
	v_rcp_f32_e32 v66, v59
	s_nop 0
	v_mul_f32_e32 v57, v57, v66
	v_and_b32_e32 v53, 0xffff0000, v53
	v_exp_f32_e32 v66, v56
	v_mul_f32_e32 v56, 0xbfb8aa3b, v80
	v_exp_f32_e32 v67, v56
	v_rcp_f32_e32 v56, v58
	s_nop 0
	v_mul_f32_e32 v56, v77, v56
	v_lshlrev_b32_e32 v89, 16, v52
	ds_read2_b32 v[46:47], v158 offset0:6 offset1:7
	ds_read2_b32 v[60:61], v158 offset0:4 offset1:5
	ds_read2_b32 v[62:63], v158 offset0:2 offset1:3
	ds_read2_b32 v[64:65], v158 offset1:1
	v_pk_add_f32 v[66:67], v[66:67], 1.0 op_sel_hi:[1,0]
	ds_read2_b32 v[68:69], v158 offset0:14 offset1:15
	ds_read2_b32 v[70:71], v158 offset0:12 offset1:13
	ds_read2_b32 v[72:73], v158 offset0:10 offset1:11
	ds_read2_b32 v[74:75], v158 offset0:8 offset1:9
	s_waitcnt lgkmcnt(4)
	v_add_f32_e32 v32, 0, v64
	v_add_f32_e32 v32, v32, v65
	v_add_f32_e32 v32, v32, v62
	v_rcp_f32_e32 v59, v67
	s_nop 0
	v_mul_f32_e32 v59, v80, v59
	v_add_f32_e32 v32, v32, v63
	v_rcp_f32_e32 v58, v66
	s_nop 0
	v_mul_f32_e32 v58, v79, v58
	v_mul_f32_e32 v66, 0xbfb8aa3b, v78
	v_mul_f32_e32 v67, 0xbfb8aa3b, v76
	v_exp_f32_e32 v66, v66
	v_exp_f32_e32 v67, v67
	v_add_f32_e32 v32, v32, v60
	v_add_f32_e32 v32, v32, v61
	v_add_f32_e32 v32, v32, v46
	v_pk_add_f32 v[66:67], v[66:67], 1.0 op_sel_hi:[1,0]
	v_add_f32_e32 v32, v32, v47
	s_waitcnt lgkmcnt(0)
	v_add_f32_e32 v32, v32, v74
	v_add_f32_e32 v32, v32, v75
	v_add_f32_e32 v32, v32, v72
	v_rcp_f32_e32 v77, v67
	s_nop 0
	v_mul_f32_e32 v67, v76, v77
	v_mul_f32_e32 v76, 0xbfb8aa3b, v83
	v_mul_f32_e32 v77, 0xbfb8aa3b, v54
	v_exp_f32_e32 v76, v76
	v_exp_f32_e32 v77, v77
	v_rcp_f32_e32 v79, v66
	s_nop 0
	v_mul_f32_e32 v66, v78, v79
	v_pk_add_f32 v[76:77], v[76:77], 1.0 op_sel_hi:[1,0]
	v_add_f32_e32 v32, v32, v73
	v_add_f32_e32 v32, v32, v70
	v_add_f32_e32 v32, v32, v71
	v_add_f32_e32 v32, v32, v68
	v_mul_f32_e32 v78, 0xbfb8aa3b, v88
	v_mul_f32_e32 v79, 0xbfb8aa3b, v53
	v_rcp_f32_e32 v55, v77
	s_nop 0
	v_mul_f32_e32 v55, v54, v55
	v_exp_f32_e32 v78, v78
	v_exp_f32_e32 v79, v79
	s_nop 0
	v_pk_add_f32 v[78:79], v[78:79], 1.0 op_sel_hi:[1,0]
	v_rcp_f32_e32 v54, v76
	s_nop 0
	v_mul_f32_e32 v54, v83, v54
	v_add_f32_e32 v32, v32, v69
	v_rcp_f32_e32 v77, v79
	s_nop 0
	v_mul_f32_e32 v77, v53, v77
	s_mov_b32 s37, 0
	v_and_b32_e32 v79, 0xffff0000, v52
	v_mul_f32_e32 v52, 0xbfb8aa3b, v89
	v_mul_f32_e32 v53, 0xbfb8aa3b, v79
	v_exp_f32_e32 v52, v52
	v_exp_f32_e32 v53, v53
	v_rcp_f32_e32 v76, v78
	s_nop 0
	v_mul_f32_e32 v76, v88, v76
	ds_read2_b32 v[80:81], v158 offset0:22 offset1:23
	ds_read2_b32 v[82:83], v158 offset0:20 offset1:21
	ds_read2_b32 v[84:85], v158 offset0:18 offset1:19
	ds_read2_b32 v[86:87], v158 offset0:16 offset1:17
	v_lshl_add_u64 v[34:35], v[34:35], 0, s[36:37]
	v_pk_add_f32 v[52:53], v[52:53], 1.0 op_sel_hi:[1,0]
	v_mov_b32_e32 v115, v33
	s_waitcnt lgkmcnt(0)
	v_add_f32_e32 v32, v32, v86
	v_add_f32_e32 v32, v32, v87
	v_add_f32_e32 v32, v32, v84
	v_rcp_f32_e32 v78, v53
	s_nop 0
	v_mul_f32_e32 v79, v79, v78
	v_add_f32_e32 v32, v32, v85
	v_rcp_f32_e32 v78, v52
	s_nop 0
	v_mul_f32_e32 v78, v89, v78
	v_mul_f32_e32 v52, 0xbfb8aa3b, v113
	v_mul_f32_e32 v53, 0xbfb8aa3b, v124
	v_exp_f32_e32 v52, v52
	v_exp_f32_e32 v53, v53
	v_add_f32_e32 v32, v32, v82
	v_add_f32_e32 v32, v32, v83
	v_add_f32_e32 v32, v32, v80
	v_pk_add_f32 v[88:89], v[52:53], 1.0 op_sel_hi:[1,0]
	ds_read2_b32 v[90:91], v158 offset0:30 offset1:31
	ds_read2_b32 v[52:53], v158 offset0:28 offset1:29
	ds_read2_b32 v[92:93], v158 offset0:26 offset1:27
	ds_read2_b32 v[94:95], v158 offset0:24 offset1:25
	v_add_f32_e32 v32, v32, v81
	s_waitcnt lgkmcnt(0)
	v_add_f32_e32 v32, v32, v94
	v_add_f32_e32 v32, v32, v95
	v_add_f32_e32 v32, v32, v92
	v_add_f32_e32 v32, v32, v93
	v_add_f32_e32 v32, v32, v52
	v_add_f32_e32 v32, v32, v53
	v_add_f32_e32 v32, v32, v90
	v_add_f32_e32 v32, v32, v91
	ds_bpermute_b32 v97, v157, v32
	s_waitcnt lgkmcnt(0)
	v_add_f32_e32 v32, v32, v97
	ds_bpermute_b32 v97, v156, v32
	v_lshl_add_u64 v[34:35], v[34:35], 0, v[114:115]
	s_waitcnt lgkmcnt(0)
	v_add_f32_e32 v32, v32, v97
	v_mul_f32_e32 v32, 0x3c000000, v32
	v_pk_add_f32 v[64:65], v[64:65], v[32:33] op_sel_hi:[1,0] neg_lo:[0,1] neg_hi:[0,1]
	v_pk_add_f32 v[62:63], v[62:63], v[32:33] op_sel_hi:[1,0] neg_lo:[0,1] neg_hi:[0,1]
	v_pk_mul_f32 v[96:97], v[64:65], v[64:65]
	v_pk_mul_f32 v[98:99], v[62:63], v[62:63]
	v_pk_add_f32 v[100:101], v[60:61], v[32:33] op_sel_hi:[1,0] neg_lo:[0,1] neg_hi:[0,1]
	v_pk_add_f32 v[104:105], v[46:47], v[32:33] op_sel_hi:[1,0] neg_lo:[0,1] neg_hi:[0,1]
	v_pk_add_f32 v[74:75], v[74:75], v[32:33] op_sel_hi:[1,0] neg_lo:[0,1] neg_hi:[0,1]
	v_pk_add_f32 v[72:73], v[72:73], v[32:33] op_sel_hi:[1,0] neg_lo:[0,1] neg_hi:[0,1]
	v_pk_add_f32 v[70:71], v[70:71], v[32:33] op_sel_hi:[1,0] neg_lo:[0,1] neg_hi:[0,1]
	v_pk_add_f32 v[68:69], v[68:69], v[32:33] op_sel_hi:[1,0] neg_lo:[0,1] neg_hi:[0,1]
	v_pk_add_f32 v[86:87], v[86:87], v[32:33] op_sel_hi:[1,0] neg_lo:[0,1] neg_hi:[0,1]
	v_pk_add_f32 v[84:85], v[84:85], v[32:33] op_sel_hi:[1,0] neg_lo:[0,1] neg_hi:[0,1]
	v_pk_add_f32 v[82:83], v[82:83], v[32:33] op_sel_hi:[1,0] neg_lo:[0,1] neg_hi:[0,1]
	v_pk_add_f32 v[80:81], v[80:81], v[32:33] op_sel_hi:[1,0] neg_lo:[0,1] neg_hi:[0,1]
	v_pk_add_f32 v[94:95], v[94:95], v[32:33] op_sel_hi:[1,0] neg_lo:[0,1] neg_hi:[0,1]
	v_pk_add_f32 v[60:61], v[92:93], v[32:33] op_sel_hi:[1,0] neg_lo:[0,1] neg_hi:[0,1]
	v_pk_add_f32 v[52:53], v[52:53], v[32:33] op_sel_hi:[1,0] neg_lo:[0,1] neg_hi:[0,1]
	v_pk_add_f32 v[46:47], v[90:91], v[32:33] op_sel_hi:[1,0] neg_lo:[0,1] neg_hi:[0,1]
	v_add_f32_e32 v32, v96, v97
	v_add_f32_e32 v32, v98, v32
	v_pk_mul_f32 v[102:103], v[100:101], v[100:101]
	v_add_f32_e32 v32, v99, v32
	v_add_f32_e32 v32, v102, v32
	v_pk_mul_f32 v[106:107], v[104:105], v[104:105]
	v_add_f32_e32 v32, v103, v32
	v_add_f32_e32 v32, v106, v32
	v_pk_mul_f32 v[108:109], v[74:75], v[74:75]
	v_add_f32_e32 v32, v107, v32
	v_add_f32_e32 v32, v108, v32
	v_pk_mul_f32 v[110:111], v[72:73], v[72:73]
	v_add_f32_e32 v32, v109, v32
	v_add_f32_e32 v32, v110, v32
	v_pk_mul_f32 v[114:115], v[70:71], v[70:71]
	v_add_f32_e32 v32, v111, v32
	v_add_f32_e32 v32, v114, v32
	v_pk_mul_f32 v[116:117], v[68:69], v[68:69]
	v_add_f32_e32 v32, v115, v32
	v_add_f32_e32 v32, v116, v32
	v_pk_mul_f32 v[118:119], v[86:87], v[86:87]
	v_add_f32_e32 v32, v117, v32
	v_add_f32_e32 v32, v118, v32
	v_pk_mul_f32 v[120:121], v[84:85], v[84:85]
	v_add_f32_e32 v32, v119, v32
	v_add_f32_e32 v32, v120, v32
	v_pk_mul_f32 v[122:123], v[82:83], v[82:83]
	v_add_f32_e32 v32, v121, v32
	v_add_f32_e32 v32, v122, v32
	v_pk_mul_f32 v[126:127], v[80:81], v[80:81]
	v_add_f32_e32 v32, v123, v32
	v_add_f32_e32 v32, v126, v32
	v_pk_mul_f32 v[128:129], v[94:95], v[94:95]
	v_add_f32_e32 v32, v127, v32
	v_add_f32_e32 v32, v128, v32
	v_pk_mul_f32 v[92:93], v[60:61], v[60:61]
	v_add_f32_e32 v32, v129, v32
	v_add_f32_e32 v32, v92, v32
	v_pk_mul_f32 v[130:131], v[52:53], v[52:53]
	v_add_f32_e32 v32, v93, v32
	v_add_f32_e32 v32, v130, v32
	v_pk_mul_f32 v[90:91], v[46:47], v[46:47]
	v_add_f32_e32 v32, v131, v32
	v_add_f32_e32 v32, v90, v32
	v_add_f32_e32 v32, v91, v32
	ds_bpermute_b32 v90, v157, v32
	s_mov_b32 s0, 0xf800000
	v_rcp_f32_e32 v91, v89
	s_nop 0
	v_mul_f32_e32 v89, v124, v91
	s_waitcnt lgkmcnt(0)
	v_add_f32_e32 v32, v32, v90
	ds_bpermute_b32 v90, v156, v32
	s_waitcnt lgkmcnt(0)
	v_add_f32_e32 v32, v32, v90
	v_mov_b32_e32 v90, 0x358637bd
	v_fmac_f32_e32 v90, 0x3c000000, v32
	v_mul_f32_e32 v32, 0x4f800000, v90
	v_cmp_gt_f32_e64 s[0:1], s0, v90
	s_nop 1
	v_cndmask_b32_e64 v32, v90, v32, s[0:1]
	v_sqrt_f32_e32 v90, v32
	v_readlane_b32 s5, v254, 1
	v_add_u32_e32 v93, -1, v90
	v_fma_f32 v96, -v93, v90, v32
	v_cmp_ge_f32_e64 s[4:5], 0, v96
	v_add_u32_e32 v96, 1, v90
	s_nop 1
	v_cndmask_b32_e64 v93, v90, v93, s[4:5]
	v_fma_f32 v90, -v96, v90, v32
	v_cmp_lt_f32_e64 s[4:5], 0, v90
	v_rcp_f32_e32 v91, v88
	s_nop 0
	v_mul_f32_e32 v88, v113, v91
	s_movk_i32 s2, 0x37ff
	v_cndmask_b32_e64 v90, v93, v96, s[4:5]
	v_mul_f32_e32 v93, 0x37800000, v90
	v_cndmask_b32_e64 v90, v90, v93, s[0:1]
	v_mov_b32_e32 v93, 0x260
	v_cmp_class_f32_e64 s[0:1], v32, v93
	s_nop 1
	v_cndmask_b32_e64 v32, v90, v32, s[0:1]
	v_rcp_f32_e32 v32, v32
	s_nop 0
	v_pk_mul_f32 v[64:65], v[64:65], v[32:33] op_sel_hi:[1,0]
	s_waitcnt vmcnt(4)
	v_pk_mul_f32 v[28:29], v[28:29], v[64:65]
	s_nop 0
	v_pk_mul_f32 v[28:29], v[40:41], v[28:29]
	v_pk_mul_f32 v[40:41], v[62:63], v[32:33] op_sel_hi:[1,0]
	s_nop 0
	v_pk_mul_f32 v[30:31], v[30:31], v[40:41]
	s_nop 0
	v_pk_mul_f32 v[30:31], v[38:39], v[30:31]
	v_pk_mul_f32 v[38:39], v[100:101], v[32:33] op_sel_hi:[1,0]
	s_nop 0
	v_pk_mul_f32 v[24:25], v[24:25], v[38:39]
	s_nop 0
	v_pk_mul_f32 v[36:37], v[36:37], v[24:25]
	v_pk_mul_f32 v[24:25], v[104:105], v[32:33] op_sel_hi:[1,0]
	s_nop 0
	v_pk_mul_f32 v[24:25], v[26:27], v[24:25]
	v_cvt_pk_bf16_f32 v26, v36, v37
	v_pk_mul_f32 v[38:39], v[42:43], v[24:25]
	v_cvt_pk_bf16_f32 v24, v28, v29
	v_cvt_pk_bf16_f32 v25, v30, v31
	v_cvt_pk_bf16_f32 v27, v38, v39
	global_store_dwordx4 v[34:35], v[24:27], off
	s_nop 1
	v_pk_mul_f32 v[24:25], v[74:75], v[32:33] op_sel_hi:[1,0]
	s_nop 0
	v_pk_mul_f32 v[20:21], v[20:21], v[24:25]
	v_pk_mul_f32 v[24:25], v[72:73], v[32:33] op_sel_hi:[1,0]
	v_pk_mul_f32 v[20:21], v[58:59], v[20:21]
	v_pk_mul_f32 v[22:23], v[22:23], v[24:25]
	v_pk_mul_f32 v[24:25], v[70:71], v[32:33] op_sel_hi:[1,0]
	v_pk_mul_f32 v[22:23], v[56:57], v[22:23]
	v_pk_mul_f32 v[16:17], v[16:17], v[24:25]
	s_nop 0
	v_pk_mul_f32 v[24:25], v[44:45], v[16:17]
	v_pk_mul_f32 v[16:17], v[68:69], v[32:33] op_sel_hi:[1,0]
	s_nop 0
	v_pk_mul_f32 v[16:17], v[18:19], v[16:17]
	v_cvt_pk_bf16_f32 v18, v24, v25
	v_pk_mul_f32 v[26:27], v[66:67], v[16:17]
	v_cvt_pk_bf16_f32 v16, v20, v21
	v_cvt_pk_bf16_f32 v17, v22, v23
	v_cvt_pk_bf16_f32 v19, v26, v27
	global_store_dwordx4 v[34:35], v[16:19], off offset:16
	v_lshlrev_b32_e32 v20, 16, v48
	v_and_b32_e32 v21, 0xffff0000, v48
	v_pk_mul_f32 v[16:17], v[86:87], v[32:33] op_sel_hi:[1,0]
	s_waitcnt vmcnt(2)
	v_pk_mul_f32 v[12:13], v[12:13], v[16:17]
	v_pk_mul_f32 v[16:17], v[84:85], v[32:33] op_sel_hi:[1,0]
	v_pk_mul_f32 v[12:13], v[78:79], v[12:13]
	v_pk_mul_f32 v[14:15], v[14:15], v[16:17]
	v_pk_mul_f32 v[16:17], v[82:83], v[32:33] op_sel_hi:[1,0]
	v_pk_mul_f32 v[14:15], v[76:77], v[14:15]
	v_pk_mul_f32 v[8:9], v[8:9], v[16:17]
	s_nop 0
	v_pk_mul_f32 v[16:17], v[54:55], v[8:9]
	v_pk_mul_f32 v[8:9], v[80:81], v[32:33] op_sel_hi:[1,0]
	s_nop 0
	v_pk_mul_f32 v[8:9], v[10:11], v[8:9]
	v_mul_f32_e32 v10, 0xbfb8aa3b, v20
	v_mul_f32_e32 v11, 0xbfb8aa3b, v21
	v_exp_f32_e32 v10, v10
	v_exp_f32_e32 v11, v11
	v_pk_mul_f32 v[18:19], v[88:89], v[8:9]
	v_cvt_pk_bf16_f32 v8, v12, v13
	v_cvt_pk_bf16_f32 v9, v14, v15
	v_pk_add_f32 v[12:13], v[10:11], 1.0 op_sel_hi:[1,0]
	v_cvt_pk_bf16_f32 v10, v16, v17
	v_cvt_pk_bf16_f32 v11, v18, v19
	global_store_dwordx4 v[34:35], v[8:11], off offset:32
	v_and_b32_e32 v16, 0xffff0000, v49
	s_nop 0
	v_rcp_f32_e32 v9, v13
	s_nop 0
	v_mul_f32_e32 v9, v21, v9
	v_lshlrev_b32_e32 v15, 16, v49
	v_mul_f32_e32 v10, 0xbfb8aa3b, v15
	v_mul_f32_e32 v11, 0xbfb8aa3b, v16
	v_exp_f32_e32 v10, v10
	v_exp_f32_e32 v11, v11
	v_rcp_f32_e32 v8, v12
	s_nop 0
	v_mul_f32_e32 v8, v20, v8
	v_pk_mul_f32 v[12:13], v[94:95], v[32:33] op_sel_hi:[1,0]
	v_pk_add_f32 v[10:11], v[10:11], 1.0 op_sel_hi:[1,0]
	v_pk_mul_f32 v[4:5], v[4:5], v[12:13]
	v_pk_mul_f32 v[4:5], v[8:9], v[4:5]
	v_rcp_f32_e32 v9, v11
	s_nop 0
	v_mul_f32_e32 v9, v16, v9
	v_lshlrev_b32_e32 v16, 16, v50
	v_and_b32_e32 v17, 0xffff0000, v50
	v_mul_f32_e32 v12, 0xbfb8aa3b, v16
	v_mul_f32_e32 v13, 0xbfb8aa3b, v17
	v_exp_f32_e32 v12, v12
	v_exp_f32_e32 v13, v13
	v_rcp_f32_e32 v8, v10
	s_nop 0
	v_mul_f32_e32 v8, v15, v8
	v_pk_add_f32 v[10:11], v[12:13], 1.0 op_sel_hi:[1,0]
	s_nop 0
	v_pk_mul_f32 v[12:13], v[60:61], v[32:33] op_sel_hi:[1,0]
	s_nop 0
	v_pk_mul_f32 v[6:7], v[6:7], v[12:13]
	s_nop 0
	v_pk_mul_f32 v[6:7], v[8:9], v[6:7]
	v_rcp_f32_e32 v9, v11
	s_nop 0
	v_mul_f32_e32 v9, v17, v9
	v_lshlrev_b32_e32 v15, 16, v51
	v_and_b32_e32 v17, 0xffff0000, v51
	v_mul_f32_e32 v12, 0xbfb8aa3b, v15
	v_mul_f32_e32 v13, 0xbfb8aa3b, v17
	v_exp_f32_e32 v12, v12
	v_exp_f32_e32 v13, v13
	v_rcp_f32_e32 v8, v10
	s_nop 0
	v_mul_f32_e32 v8, v16, v8
	v_pk_add_f32 v[10:11], v[12:13], 1.0 op_sel_hi:[1,0]
	s_nop 0
	v_pk_mul_f32 v[12:13], v[52:53], v[32:33] op_sel_hi:[1,0]
	s_nop 0
	v_pk_mul_f32 v[0:1], v[0:1], v[12:13]
	s_nop 0
	v_pk_mul_f32 v[8:9], v[8:9], v[0:1]
	v_rcp_f32_e32 v1, v11
	s_nop 0
	v_mul_f32_e32 v1, v17, v1
	v_rcp_f32_e32 v0, v10
	s_nop 0
	v_mul_f32_e32 v0, v15, v0
	v_pk_mul_f32 v[10:11], v[46:47], v[32:33] op_sel_hi:[1,0]
	s_mov_b64 s[0:1], 0x3300000
	v_pk_mul_f32 v[2:3], v[2:3], v[10:11]
	s_nop 0
	v_pk_mul_f32 v[10:11], v[0:1], v[2:3]
	v_cvt_pk_bf16_f32 v0, v4, v5
	v_cvt_pk_bf16_f32 v1, v6, v7
	v_cvt_pk_bf16_f32 v2, v8, v9
	v_cvt_pk_bf16_f32 v3, v10, v11
	global_store_dwordx4 v[34:35], v[0:3], off offset:48
	v_lshl_add_u32 v5, s52, 9, v226
	s_waitcnt lgkmcnt(0)
	s_barrier
	s_lshr_b32 s0, s88, 5
	s_lshl_b32 s1, s0, 3
	s_add_i32 s1, s1, s53
	s_lshl_b32 s2, s1, 8
	s_lshl_b32 s3, s52, 3
	s_add_i32 s2, s2, s3
	v_readlane_b32 s8, v254, 2
	v_readlane_b32 s9, v254, 3
	v_lshrrev_b32_e32 v22, 6, v226
	v_add_u32_e32 v23, s2, v22
	v_and_b32_e32 v32, 63, v226
	v_lshlrev_b32_e32 v32, 4, v32
	v_bfe_u32 v33, v226, 3, 3
	v_lshlrev_b32_e32 v33, 2, v33
	v_lshl_add_u32 v0, v23, 5, v33
	v_add_u32_e32 v0, 0x3300000, v0
	v_add_u32_e32 v1, 0x1000, v0
	v_add_u32_e32 v2, 0x80000, v0
	v_add_u32_e32 v3, 0x81000, v0
	v_add_u32_e32 v4, 0x100000, v0
	v_add_u32_e32 v5, 0x101000, v0
	v_lshl_add_u32 v6, v23, 10, v32
	v_add_u32_e32 v6, 0xb500000, v6
	v_add_u32_e32 v7, s3, v22
	v_lshl_add_u32 v7, v7, 11, v32
	s_lshl_b32 s2, s1, 20
	s_add_u32 s8, s8, s2
	s_addc_u32 s9, s9, 0
	global_load_dword v60, v0, s[96:97]
	global_load_dword v61, v2, s[96:97]
	global_load_dword v62, v4, s[96:97]
	global_load_dwordx4 v[48:51], v6, s[96:97]
	v_add_u32_e32 v8, 0x1000000, v6
	global_load_dwordx4 v[52:55], v8, s[96:97]
	v_add_u32_e32 v8, 0x2000000, v6
	global_load_dwordx4 v[56:59], v8, s[96:97]
	global_load_dword v76, v0, s[96:97] offset:1024
	global_load_dword v77, v2, s[96:97] offset:1024
	global_load_dword v78, v4, s[96:97] offset:1024
	v_add_u32_e32 v8, 0x8000, v6
	global_load_dwordx4 v[64:67], v8, s[96:97]
	v_add_u32_e32 v8, 0x1008000, v6
	global_load_dwordx4 v[68:71], v8, s[96:97]
	v_add_u32_e32 v8, 0x2008000, v6
	global_load_dwordx4 v[72:75], v8, s[96:97]
	global_load_dword v92, v0, s[96:97] offset:2048
	global_load_dword v93, v2, s[96:97] offset:2048
	global_load_dword v94, v4, s[96:97] offset:2048
	v_add_u32_e32 v8, 0x10000, v6
	global_load_dwordx4 v[80:83], v8, s[96:97]
	v_add_u32_e32 v8, 0x1010000, v6
	global_load_dwordx4 v[84:87], v8, s[96:97]
	v_add_u32_e32 v8, 0x2010000, v6
	global_load_dwordx4 v[88:91], v8, s[96:97]
	global_load_dword v108, v0, s[96:97] offset:3072
	global_load_dword v109, v2, s[96:97] offset:3072
	global_load_dword v110, v4, s[96:97] offset:3072
	v_add_u32_e32 v8, 0x18000, v6
	global_load_dwordx4 v[96:99], v8, s[96:97]
	v_add_u32_e32 v8, 0x1018000, v6
	global_load_dwordx4 v[100:103], v8, s[96:97]
	v_add_u32_e32 v8, 0x2018000, v6
	global_load_dwordx4 v[104:107], v8, s[96:97]
	global_load_dword v140, v1, s[96:97]
	global_load_dword v141, v3, s[96:97]
	global_load_dword v142, v5, s[96:97]
	v_add_u32_e32 v8, 0x20000, v6
	global_load_dwordx4 v[128:131], v8, s[96:97]
	v_add_u32_e32 v8, 0x1020000, v6
	global_load_dwordx4 v[132:135], v8, s[96:97]
	v_add_u32_e32 v8, 0x2020000, v6
	global_load_dwordx4 v[136:139], v8, s[96:97]
	global_load_dword v164, v1, s[96:97] offset:1024
	global_load_dword v165, v3, s[96:97] offset:1024
	global_load_dword v166, v5, s[96:97] offset:1024
	v_add_u32_e32 v8, 0x28000, v6
	global_load_dwordx4 v[152:155], v8, s[96:97]
	v_add_u32_e32 v8, 0x1028000, v6
	global_load_dwordx4 v[156:159], v8, s[96:97]
	v_add_u32_e32 v8, 0x2028000, v6
	global_load_dwordx4 v[160:163], v8, s[96:97]
	global_load_dword v218, v1, s[96:97] offset:2048
	global_load_dword v219, v3, s[96:97] offset:2048
	global_load_dword v220, v5, s[96:97] offset:2048
	v_add_u32_e32 v8, 0x30000, v6
	global_load_dwordx4 v[206:209], v8, s[96:97]
	v_add_u32_e32 v8, 0x1030000, v6
	global_load_dwordx4 v[210:213], v8, s[96:97]
	v_add_u32_e32 v8, 0x2030000, v6
	global_load_dwordx4 v[214:217], v8, s[96:97]
	global_load_dword v244, v1, s[96:97] offset:3072
	global_load_dword v245, v3, s[96:97] offset:3072
	global_load_dword v246, v5, s[96:97] offset:3072
	v_add_u32_e32 v8, 0x38000, v6
	global_load_dwordx4 v[232:235], v8, s[96:97]
	v_add_u32_e32 v8, 0x1038000, v6
	global_load_dwordx4 v[236:239], v8, s[96:97]
	v_add_u32_e32 v8, 0x2038000, v6
	global_load_dwordx4 v[240:243], v8, s[96:97]
	s_waitcnt vmcnt(42)
	v_max3_f32 v5, v60, v61, v62
	v_sub_f32_e32 v9, v60, v5
	v_sub_f32_e32 v40, v61, v5
	v_and_b32_e32 v27, 0xffff0000, v49
	v_lshlrev_b32_e32 v28, 16, v49
	v_sub_f32_e32 v5, v62, v5
	v_lshlrev_b32_e32 v24, 16, v52
	v_and_b32_e32 v11, 0xffff0000, v52
	v_lshlrev_b32_e32 v38, 16, v56
	v_and_b32_e32 v39, 0xffff0000, v56
	v_lshlrev_b32_e32 v26, 16, v53
	v_and_b32_e32 v29, 0xffff0000, v53
	v_lshlrev_b32_e32 v14, 16, v57
	v_and_b32_e32 v15, 0xffff0000, v57
	v_lshlrev_b32_e32 v18, 16, v58
	v_and_b32_e32 v19, 0xffff0000, v58
	v_mul_f32_e32 v9, 0x3fb8aa3b, v9
	v_mul_f32_e32 v20, 0x3fb8aa3b, v40
	v_and_b32_e32 v35, 0xffff0000, v51
	v_lshlrev_b32_e32 v36, 16, v51
	v_lshlrev_b32_e32 v30, 16, v54
	v_and_b32_e32 v13, 0xffff0000, v54
	v_lshlrev_b32_e32 v34, 16, v55
	v_and_b32_e32 v37, 0xffff0000, v55
	v_lshlrev_b32_e32 v16, 16, v59
	v_and_b32_e32 v17, 0xffff0000, v59
	v_mul_f32_e32 v5, 0x3fb8aa3b, v5
	v_exp_f32_e32 v21, v9
	v_exp_f32_e32 v20, v20
	v_exp_f32_e32 v5, v5
	v_and_b32_e32 v25, 0xffff0000, v48
	v_lshlrev_b32_e32 v10, 16, v48
	v_add_f32_e32 v9, v21, v20
	v_add_f32_e32 v9, v5, v9
	v_and_b32_e32 v31, 0xffff0000, v50
	v_rcp_f32_e32 v40, v9
	s_nop 0
	v_lshlrev_b32_e32 v12, 16, v50
	v_pk_mul_f32 v[20:21], v[20:21], v[40:41] op_sel_hi:[1,0]
	v_mul_f32_e32 v42, v5, v40
	v_pk_mul_f32 v[10:11], v[20:21], v[10:11] op_sel:[1,0] op_sel_hi:[0,1]
	v_pk_mul_f32 v[28:29], v[20:21], v[28:29] op_sel:[1,0] op_sel_hi:[0,1]
	v_pk_mul_f32 v[12:13], v[20:21], v[12:13] op_sel:[1,0] op_sel_hi:[0,1]
	v_pk_mul_f32 v[36:37], v[20:21], v[36:37] op_sel:[1,0] op_sel_hi:[0,1]
	v_pk_fma_f32 v[10:11], v[20:21], v[24:25], v[10:11]
	v_pk_fma_f32 v[24:25], v[20:21], v[26:27], v[28:29]
	v_pk_fma_f32 v[12:13], v[20:21], v[30:31], v[12:13]
	v_pk_fma_f32 v[20:21], v[20:21], v[34:35], v[36:37]
	v_pk_fma_f32 v[10:11], v[42:43], v[38:39], v[10:11] op_sel_hi:[0,1,1]
	v_pk_fma_f32 v[14:15], v[42:43], v[14:15], v[24:25] op_sel_hi:[0,1,1]
	v_pk_fma_f32 v[12:13], v[42:43], v[18:19], v[12:13] op_sel_hi:[0,1,1]
	v_pk_fma_f32 v[16:17], v[42:43], v[16:17], v[20:21] op_sel_hi:[0,1,1]
	v_cvt_pk_bf16_f32 v10, v10, v11
	v_cvt_pk_bf16_f32 v11, v14, v15
	v_cvt_pk_bf16_f32 v12, v12, v13
	v_cvt_pk_bf16_f32 v13, v16, v17
	global_store_dwordx4 v7, v[10:13], s[8:9] offset:1024
	s_waitcnt vmcnt(37)
	v_max3_f32 v5, v76, v77, v78
	v_sub_f32_e32 v9, v76, v5
	v_sub_f32_e32 v40, v77, v5
	v_and_b32_e32 v27, 0xffff0000, v65
	v_lshlrev_b32_e32 v28, 16, v65
	v_sub_f32_e32 v5, v78, v5
	v_lshlrev_b32_e32 v24, 16, v68
	v_and_b32_e32 v11, 0xffff0000, v68
	v_lshlrev_b32_e32 v38, 16, v72
	v_and_b32_e32 v39, 0xffff0000, v72
	v_lshlrev_b32_e32 v26, 16, v69
	v_and_b32_e32 v29, 0xffff0000, v69
	v_lshlrev_b32_e32 v14, 16, v73
	v_and_b32_e32 v15, 0xffff0000, v73
	v_lshlrev_b32_e32 v18, 16, v74
	v_and_b32_e32 v19, 0xffff0000, v74
	v_mul_f32_e32 v9, 0x3fb8aa3b, v9
	v_mul_f32_e32 v20, 0x3fb8aa3b, v40
	v_and_b32_e32 v35, 0xffff0000, v67
	v_lshlrev_b32_e32 v36, 16, v67
	v_lshlrev_b32_e32 v30, 16, v70
	v_and_b32_e32 v13, 0xffff0000, v70
	v_lshlrev_b32_e32 v34, 16, v71
	v_and_b32_e32 v37, 0xffff0000, v71
	v_lshlrev_b32_e32 v16, 16, v75
	v_and_b32_e32 v17, 0xffff0000, v75
	v_mul_f32_e32 v5, 0x3fb8aa3b, v5
	v_exp_f32_e32 v21, v9
	v_exp_f32_e32 v20, v20
	v_exp_f32_e32 v5, v5
	v_and_b32_e32 v25, 0xffff0000, v64
	v_lshlrev_b32_e32 v10, 16, v64
	v_add_f32_e32 v9, v21, v20
	v_add_f32_e32 v9, v5, v9
	v_and_b32_e32 v31, 0xffff0000, v66
	v_rcp_f32_e32 v40, v9
	s_nop 0
	v_lshlrev_b32_e32 v12, 16, v66
	v_pk_mul_f32 v[20:21], v[20:21], v[40:41] op_sel_hi:[1,0]
	v_mul_f32_e32 v42, v5, v40
	v_pk_mul_f32 v[10:11], v[20:21], v[10:11] op_sel:[1,0] op_sel_hi:[0,1]
	v_pk_mul_f32 v[28:29], v[20:21], v[28:29] op_sel:[1,0] op_sel_hi:[0,1]
	v_pk_mul_f32 v[12:13], v[20:21], v[12:13] op_sel:[1,0] op_sel_hi:[0,1]
	v_pk_mul_f32 v[36:37], v[20:21], v[36:37] op_sel:[1,0] op_sel_hi:[0,1]
	v_pk_fma_f32 v[10:11], v[20:21], v[24:25], v[10:11]
	v_pk_fma_f32 v[24:25], v[20:21], v[26:27], v[28:29]
	v_pk_fma_f32 v[12:13], v[20:21], v[30:31], v[12:13]
	v_pk_fma_f32 v[20:21], v[20:21], v[34:35], v[36:37]
	v_pk_fma_f32 v[10:11], v[42:43], v[38:39], v[10:11] op_sel_hi:[0,1,1]
	v_pk_fma_f32 v[14:15], v[42:43], v[14:15], v[24:25] op_sel_hi:[0,1,1]
	v_pk_fma_f32 v[12:13], v[42:43], v[18:19], v[12:13] op_sel_hi:[0,1,1]
	v_pk_fma_f32 v[16:17], v[42:43], v[16:17], v[20:21] op_sel_hi:[0,1,1]
	v_cvt_pk_bf16_f32 v10, v10, v11
	v_cvt_pk_bf16_f32 v11, v14, v15
	v_cvt_pk_bf16_f32 v12, v12, v13
	v_cvt_pk_bf16_f32 v13, v16, v17
	v_add_u32_e32 v8, 0x10000, v7
	global_store_dwordx4 v8, v[10:13], s[8:9] offset:1024
	s_waitcnt vmcnt(32)
	v_max3_f32 v5, v92, v93, v94
	v_sub_f32_e32 v9, v92, v5
	v_sub_f32_e32 v40, v93, v5
	v_and_b32_e32 v27, 0xffff0000, v81
	v_lshlrev_b32_e32 v28, 16, v81
	v_sub_f32_e32 v5, v94, v5
	v_lshlrev_b32_e32 v24, 16, v84
	v_and_b32_e32 v11, 0xffff0000, v84
	v_lshlrev_b32_e32 v38, 16, v88
	v_and_b32_e32 v39, 0xffff0000, v88
	v_lshlrev_b32_e32 v26, 16, v85
	v_and_b32_e32 v29, 0xffff0000, v85
	v_lshlrev_b32_e32 v14, 16, v89
	v_and_b32_e32 v15, 0xffff0000, v89
	v_lshlrev_b32_e32 v18, 16, v90
	v_and_b32_e32 v19, 0xffff0000, v90
	v_mul_f32_e32 v9, 0x3fb8aa3b, v9
	v_mul_f32_e32 v20, 0x3fb8aa3b, v40
	v_and_b32_e32 v35, 0xffff0000, v83
	v_lshlrev_b32_e32 v36, 16, v83
	v_lshlrev_b32_e32 v30, 16, v86
	v_and_b32_e32 v13, 0xffff0000, v86
	v_lshlrev_b32_e32 v34, 16, v87
	v_and_b32_e32 v37, 0xffff0000, v87
	v_lshlrev_b32_e32 v16, 16, v91
	v_and_b32_e32 v17, 0xffff0000, v91
	v_mul_f32_e32 v5, 0x3fb8aa3b, v5
	v_exp_f32_e32 v21, v9
	v_exp_f32_e32 v20, v20
	v_exp_f32_e32 v5, v5
	v_and_b32_e32 v25, 0xffff0000, v80
	v_lshlrev_b32_e32 v10, 16, v80
	v_add_f32_e32 v9, v21, v20
	v_add_f32_e32 v9, v5, v9
	v_and_b32_e32 v31, 0xffff0000, v82
	v_rcp_f32_e32 v40, v9
	s_nop 0
	v_lshlrev_b32_e32 v12, 16, v82
	v_pk_mul_f32 v[20:21], v[20:21], v[40:41] op_sel_hi:[1,0]
	v_mul_f32_e32 v42, v5, v40
	v_pk_mul_f32 v[10:11], v[20:21], v[10:11] op_sel:[1,0] op_sel_hi:[0,1]
	v_pk_mul_f32 v[28:29], v[20:21], v[28:29] op_sel:[1,0] op_sel_hi:[0,1]
	v_pk_mul_f32 v[12:13], v[20:21], v[12:13] op_sel:[1,0] op_sel_hi:[0,1]
	v_pk_mul_f32 v[36:37], v[20:21], v[36:37] op_sel:[1,0] op_sel_hi:[0,1]
	v_pk_fma_f32 v[10:11], v[20:21], v[24:25], v[10:11]
	v_pk_fma_f32 v[24:25], v[20:21], v[26:27], v[28:29]
	v_pk_fma_f32 v[12:13], v[20:21], v[30:31], v[12:13]
	v_pk_fma_f32 v[20:21], v[20:21], v[34:35], v[36:37]
	v_pk_fma_f32 v[10:11], v[42:43], v[38:39], v[10:11] op_sel_hi:[0,1,1]
	v_pk_fma_f32 v[14:15], v[42:43], v[14:15], v[24:25] op_sel_hi:[0,1,1]
	v_pk_fma_f32 v[12:13], v[42:43], v[18:19], v[12:13] op_sel_hi:[0,1,1]
	v_pk_fma_f32 v[16:17], v[42:43], v[16:17], v[20:21] op_sel_hi:[0,1,1]
	v_cvt_pk_bf16_f32 v10, v10, v11
	v_cvt_pk_bf16_f32 v11, v14, v15
	v_cvt_pk_bf16_f32 v12, v12, v13
	v_cvt_pk_bf16_f32 v13, v16, v17
	v_add_u32_e32 v8, 0x20000, v7
	global_store_dwordx4 v8, v[10:13], s[8:9] offset:1024
	s_waitcnt vmcnt(27)
	v_max3_f32 v5, v108, v109, v110
	v_sub_f32_e32 v9, v108, v5
	v_sub_f32_e32 v40, v109, v5
	v_and_b32_e32 v27, 0xffff0000, v97
	v_lshlrev_b32_e32 v28, 16, v97
	v_sub_f32_e32 v5, v110, v5
	v_lshlrev_b32_e32 v24, 16, v100
	v_and_b32_e32 v11, 0xffff0000, v100
	v_lshlrev_b32_e32 v38, 16, v104
	v_and_b32_e32 v39, 0xffff0000, v104
	v_lshlrev_b32_e32 v26, 16, v101
	v_and_b32_e32 v29, 0xffff0000, v101
	v_lshlrev_b32_e32 v14, 16, v105
	v_and_b32_e32 v15, 0xffff0000, v105
	v_lshlrev_b32_e32 v18, 16, v106
	v_and_b32_e32 v19, 0xffff0000, v106
	v_mul_f32_e32 v9, 0x3fb8aa3b, v9
	v_mul_f32_e32 v20, 0x3fb8aa3b, v40
	v_and_b32_e32 v35, 0xffff0000, v99
	v_lshlrev_b32_e32 v36, 16, v99
	v_lshlrev_b32_e32 v30, 16, v102
	v_and_b32_e32 v13, 0xffff0000, v102
	v_lshlrev_b32_e32 v34, 16, v103
	v_and_b32_e32 v37, 0xffff0000, v103
	v_lshlrev_b32_e32 v16, 16, v107
	v_and_b32_e32 v17, 0xffff0000, v107
	v_mul_f32_e32 v5, 0x3fb8aa3b, v5
	v_exp_f32_e32 v21, v9
	v_exp_f32_e32 v20, v20
	v_exp_f32_e32 v5, v5
	v_and_b32_e32 v25, 0xffff0000, v96
	v_lshlrev_b32_e32 v10, 16, v96
	v_add_f32_e32 v9, v21, v20
	v_add_f32_e32 v9, v5, v9
	v_and_b32_e32 v31, 0xffff0000, v98
	v_rcp_f32_e32 v40, v9
	s_nop 0
	v_lshlrev_b32_e32 v12, 16, v98
	v_pk_mul_f32 v[20:21], v[20:21], v[40:41] op_sel_hi:[1,0]
	v_mul_f32_e32 v42, v5, v40
	v_pk_mul_f32 v[10:11], v[20:21], v[10:11] op_sel:[1,0] op_sel_hi:[0,1]
	v_pk_mul_f32 v[28:29], v[20:21], v[28:29] op_sel:[1,0] op_sel_hi:[0,1]
	v_pk_mul_f32 v[12:13], v[20:21], v[12:13] op_sel:[1,0] op_sel_hi:[0,1]
	v_pk_mul_f32 v[36:37], v[20:21], v[36:37] op_sel:[1,0] op_sel_hi:[0,1]
	v_pk_fma_f32 v[10:11], v[20:21], v[24:25], v[10:11]
	v_pk_fma_f32 v[24:25], v[20:21], v[26:27], v[28:29]
	v_pk_fma_f32 v[12:13], v[20:21], v[30:31], v[12:13]
	v_pk_fma_f32 v[20:21], v[20:21], v[34:35], v[36:37]
	v_pk_fma_f32 v[10:11], v[42:43], v[38:39], v[10:11] op_sel_hi:[0,1,1]
	v_pk_fma_f32 v[14:15], v[42:43], v[14:15], v[24:25] op_sel_hi:[0,1,1]
	v_pk_fma_f32 v[12:13], v[42:43], v[18:19], v[12:13] op_sel_hi:[0,1,1]
	v_pk_fma_f32 v[16:17], v[42:43], v[16:17], v[20:21] op_sel_hi:[0,1,1]
	v_cvt_pk_bf16_f32 v10, v10, v11
	v_cvt_pk_bf16_f32 v11, v14, v15
	v_cvt_pk_bf16_f32 v12, v12, v13
	v_cvt_pk_bf16_f32 v13, v16, v17
	v_add_u32_e32 v8, 0x30000, v7
	global_store_dwordx4 v8, v[10:13], s[8:9] offset:1024
	s_waitcnt vmcnt(22)
	v_max3_f32 v5, v140, v141, v142
	v_sub_f32_e32 v9, v140, v5
	v_sub_f32_e32 v40, v141, v5
	v_and_b32_e32 v27, 0xffff0000, v129
	v_lshlrev_b32_e32 v28, 16, v129
	v_sub_f32_e32 v5, v142, v5
	v_lshlrev_b32_e32 v24, 16, v132
	v_and_b32_e32 v11, 0xffff0000, v132
	v_lshlrev_b32_e32 v38, 16, v136
	v_and_b32_e32 v39, 0xffff0000, v136
	v_lshlrev_b32_e32 v26, 16, v133
	v_and_b32_e32 v29, 0xffff0000, v133
	v_lshlrev_b32_e32 v14, 16, v137
	v_and_b32_e32 v15, 0xffff0000, v137
	v_lshlrev_b32_e32 v18, 16, v138
	v_and_b32_e32 v19, 0xffff0000, v138
	v_mul_f32_e32 v9, 0x3fb8aa3b, v9
	v_mul_f32_e32 v20, 0x3fb8aa3b, v40
	v_and_b32_e32 v35, 0xffff0000, v131
	v_lshlrev_b32_e32 v36, 16, v131
	v_lshlrev_b32_e32 v30, 16, v134
	v_and_b32_e32 v13, 0xffff0000, v134
	v_lshlrev_b32_e32 v34, 16, v135
	v_and_b32_e32 v37, 0xffff0000, v135
	v_lshlrev_b32_e32 v16, 16, v139
	v_and_b32_e32 v17, 0xffff0000, v139
	v_mul_f32_e32 v5, 0x3fb8aa3b, v5
	v_exp_f32_e32 v21, v9
	v_exp_f32_e32 v20, v20
	v_exp_f32_e32 v5, v5
	v_and_b32_e32 v25, 0xffff0000, v128
	v_lshlrev_b32_e32 v10, 16, v128
	v_add_f32_e32 v9, v21, v20
	v_add_f32_e32 v9, v5, v9
	v_and_b32_e32 v31, 0xffff0000, v130
	v_rcp_f32_e32 v40, v9
	s_nop 0
	v_lshlrev_b32_e32 v12, 16, v130
	v_pk_mul_f32 v[20:21], v[20:21], v[40:41] op_sel_hi:[1,0]
	v_mul_f32_e32 v42, v5, v40
	v_pk_mul_f32 v[10:11], v[20:21], v[10:11] op_sel:[1,0] op_sel_hi:[0,1]
	v_pk_mul_f32 v[28:29], v[20:21], v[28:29] op_sel:[1,0] op_sel_hi:[0,1]
	v_pk_mul_f32 v[12:13], v[20:21], v[12:13] op_sel:[1,0] op_sel_hi:[0,1]
	v_pk_mul_f32 v[36:37], v[20:21], v[36:37] op_sel:[1,0] op_sel_hi:[0,1]
	v_pk_fma_f32 v[10:11], v[20:21], v[24:25], v[10:11]
	v_pk_fma_f32 v[24:25], v[20:21], v[26:27], v[28:29]
	v_pk_fma_f32 v[12:13], v[20:21], v[30:31], v[12:13]
	v_pk_fma_f32 v[20:21], v[20:21], v[34:35], v[36:37]
	v_pk_fma_f32 v[10:11], v[42:43], v[38:39], v[10:11] op_sel_hi:[0,1,1]
	v_pk_fma_f32 v[14:15], v[42:43], v[14:15], v[24:25] op_sel_hi:[0,1,1]
	v_pk_fma_f32 v[12:13], v[42:43], v[18:19], v[12:13] op_sel_hi:[0,1,1]
	v_pk_fma_f32 v[16:17], v[42:43], v[16:17], v[20:21] op_sel_hi:[0,1,1]
	v_cvt_pk_bf16_f32 v10, v10, v11
	v_cvt_pk_bf16_f32 v11, v14, v15
	v_cvt_pk_bf16_f32 v12, v12, v13
	v_cvt_pk_bf16_f32 v13, v16, v17
	v_add_u32_e32 v8, 0x40000, v7
	global_store_dwordx4 v8, v[10:13], s[8:9] offset:1024
	s_waitcnt vmcnt(17)
	v_max3_f32 v5, v164, v165, v166
	v_sub_f32_e32 v9, v164, v5
	v_sub_f32_e32 v40, v165, v5
	v_and_b32_e32 v27, 0xffff0000, v153
	v_lshlrev_b32_e32 v28, 16, v153
	v_sub_f32_e32 v5, v166, v5
	v_lshlrev_b32_e32 v24, 16, v156
	v_and_b32_e32 v11, 0xffff0000, v156
	v_lshlrev_b32_e32 v38, 16, v160
	v_and_b32_e32 v39, 0xffff0000, v160
	v_lshlrev_b32_e32 v26, 16, v157
	v_and_b32_e32 v29, 0xffff0000, v157
	v_lshlrev_b32_e32 v14, 16, v161
	v_and_b32_e32 v15, 0xffff0000, v161
	v_lshlrev_b32_e32 v18, 16, v162
	v_and_b32_e32 v19, 0xffff0000, v162
	v_mul_f32_e32 v9, 0x3fb8aa3b, v9
	v_mul_f32_e32 v20, 0x3fb8aa3b, v40
	v_and_b32_e32 v35, 0xffff0000, v155
	v_lshlrev_b32_e32 v36, 16, v155
	v_lshlrev_b32_e32 v30, 16, v158
	v_and_b32_e32 v13, 0xffff0000, v158
	v_lshlrev_b32_e32 v34, 16, v159
	v_and_b32_e32 v37, 0xffff0000, v159
	v_lshlrev_b32_e32 v16, 16, v163
	v_and_b32_e32 v17, 0xffff0000, v163
	v_mul_f32_e32 v5, 0x3fb8aa3b, v5
	v_exp_f32_e32 v21, v9
	v_exp_f32_e32 v20, v20
	v_exp_f32_e32 v5, v5
	v_and_b32_e32 v25, 0xffff0000, v152
	v_lshlrev_b32_e32 v10, 16, v152
	v_add_f32_e32 v9, v21, v20
	v_add_f32_e32 v9, v5, v9
	v_and_b32_e32 v31, 0xffff0000, v154
	v_rcp_f32_e32 v40, v9
	s_nop 0
	v_lshlrev_b32_e32 v12, 16, v154
	v_pk_mul_f32 v[20:21], v[20:21], v[40:41] op_sel_hi:[1,0]
	v_mul_f32_e32 v42, v5, v40
	v_pk_mul_f32 v[10:11], v[20:21], v[10:11] op_sel:[1,0] op_sel_hi:[0,1]
	v_pk_mul_f32 v[28:29], v[20:21], v[28:29] op_sel:[1,0] op_sel_hi:[0,1]
	v_pk_mul_f32 v[12:13], v[20:21], v[12:13] op_sel:[1,0] op_sel_hi:[0,1]
	v_pk_mul_f32 v[36:37], v[20:21], v[36:37] op_sel:[1,0] op_sel_hi:[0,1]
	v_pk_fma_f32 v[10:11], v[20:21], v[24:25], v[10:11]
	v_pk_fma_f32 v[24:25], v[20:21], v[26:27], v[28:29]
	v_pk_fma_f32 v[12:13], v[20:21], v[30:31], v[12:13]
	v_pk_fma_f32 v[20:21], v[20:21], v[34:35], v[36:37]
	v_pk_fma_f32 v[10:11], v[42:43], v[38:39], v[10:11] op_sel_hi:[0,1,1]
	v_pk_fma_f32 v[14:15], v[42:43], v[14:15], v[24:25] op_sel_hi:[0,1,1]
	v_pk_fma_f32 v[12:13], v[42:43], v[18:19], v[12:13] op_sel_hi:[0,1,1]
	v_pk_fma_f32 v[16:17], v[42:43], v[16:17], v[20:21] op_sel_hi:[0,1,1]
	v_cvt_pk_bf16_f32 v10, v10, v11
	v_cvt_pk_bf16_f32 v11, v14, v15
	v_cvt_pk_bf16_f32 v12, v12, v13
	v_cvt_pk_bf16_f32 v13, v16, v17
	v_add_u32_e32 v8, 0x50000, v7
	global_store_dwordx4 v8, v[10:13], s[8:9] offset:1024
	s_waitcnt vmcnt(12)
	v_max3_f32 v5, v218, v219, v220
	v_sub_f32_e32 v9, v218, v5
	v_sub_f32_e32 v40, v219, v5
	v_and_b32_e32 v27, 0xffff0000, v207
	v_lshlrev_b32_e32 v28, 16, v207
	v_sub_f32_e32 v5, v220, v5
	v_lshlrev_b32_e32 v24, 16, v210
	v_and_b32_e32 v11, 0xffff0000, v210
	v_lshlrev_b32_e32 v38, 16, v214
	v_and_b32_e32 v39, 0xffff0000, v214
	v_lshlrev_b32_e32 v26, 16, v211
	v_and_b32_e32 v29, 0xffff0000, v211
	v_lshlrev_b32_e32 v14, 16, v215
	v_and_b32_e32 v15, 0xffff0000, v215
	v_lshlrev_b32_e32 v18, 16, v216
	v_and_b32_e32 v19, 0xffff0000, v216
	v_mul_f32_e32 v9, 0x3fb8aa3b, v9
	v_mul_f32_e32 v20, 0x3fb8aa3b, v40
	v_and_b32_e32 v35, 0xffff0000, v209
	v_lshlrev_b32_e32 v36, 16, v209
	v_lshlrev_b32_e32 v30, 16, v212
	v_and_b32_e32 v13, 0xffff0000, v212
	v_lshlrev_b32_e32 v34, 16, v213
	v_and_b32_e32 v37, 0xffff0000, v213
	v_lshlrev_b32_e32 v16, 16, v217
	v_and_b32_e32 v17, 0xffff0000, v217
	v_mul_f32_e32 v5, 0x3fb8aa3b, v5
	v_exp_f32_e32 v21, v9
	v_exp_f32_e32 v20, v20
	v_exp_f32_e32 v5, v5
	v_and_b32_e32 v25, 0xffff0000, v206
	v_lshlrev_b32_e32 v10, 16, v206
	v_add_f32_e32 v9, v21, v20
	v_add_f32_e32 v9, v5, v9
	v_and_b32_e32 v31, 0xffff0000, v208
	v_rcp_f32_e32 v40, v9
	s_nop 0
	v_lshlrev_b32_e32 v12, 16, v208
	v_pk_mul_f32 v[20:21], v[20:21], v[40:41] op_sel_hi:[1,0]
	v_mul_f32_e32 v42, v5, v40
	v_pk_mul_f32 v[10:11], v[20:21], v[10:11] op_sel:[1,0] op_sel_hi:[0,1]
	v_pk_mul_f32 v[28:29], v[20:21], v[28:29] op_sel:[1,0] op_sel_hi:[0,1]
	v_pk_mul_f32 v[12:13], v[20:21], v[12:13] op_sel:[1,0] op_sel_hi:[0,1]
	v_pk_mul_f32 v[36:37], v[20:21], v[36:37] op_sel:[1,0] op_sel_hi:[0,1]
	v_pk_fma_f32 v[10:11], v[20:21], v[24:25], v[10:11]
	v_pk_fma_f32 v[24:25], v[20:21], v[26:27], v[28:29]
	v_pk_fma_f32 v[12:13], v[20:21], v[30:31], v[12:13]
	v_pk_fma_f32 v[20:21], v[20:21], v[34:35], v[36:37]
	v_pk_fma_f32 v[10:11], v[42:43], v[38:39], v[10:11] op_sel_hi:[0,1,1]
	v_pk_fma_f32 v[14:15], v[42:43], v[14:15], v[24:25] op_sel_hi:[0,1,1]
	v_pk_fma_f32 v[12:13], v[42:43], v[18:19], v[12:13] op_sel_hi:[0,1,1]
	v_pk_fma_f32 v[16:17], v[42:43], v[16:17], v[20:21] op_sel_hi:[0,1,1]
	v_cvt_pk_bf16_f32 v10, v10, v11
	v_cvt_pk_bf16_f32 v11, v14, v15
	v_cvt_pk_bf16_f32 v12, v12, v13
	v_cvt_pk_bf16_f32 v13, v16, v17
	v_add_u32_e32 v8, 0x60000, v7
	global_store_dwordx4 v8, v[10:13], s[8:9] offset:1024
	s_waitcnt vmcnt(7)
	v_max3_f32 v5, v244, v245, v246
	v_sub_f32_e32 v9, v244, v5
	v_sub_f32_e32 v40, v245, v5
	v_and_b32_e32 v27, 0xffff0000, v233
	v_lshlrev_b32_e32 v28, 16, v233
	v_sub_f32_e32 v5, v246, v5
	v_lshlrev_b32_e32 v24, 16, v236
	v_and_b32_e32 v11, 0xffff0000, v236
	v_lshlrev_b32_e32 v38, 16, v240
	v_and_b32_e32 v39, 0xffff0000, v240
	v_lshlrev_b32_e32 v26, 16, v237
	v_and_b32_e32 v29, 0xffff0000, v237
	v_lshlrev_b32_e32 v14, 16, v241
	v_and_b32_e32 v15, 0xffff0000, v241
	v_lshlrev_b32_e32 v18, 16, v242
	v_and_b32_e32 v19, 0xffff0000, v242
	v_mul_f32_e32 v9, 0x3fb8aa3b, v9
	v_mul_f32_e32 v20, 0x3fb8aa3b, v40
	v_and_b32_e32 v35, 0xffff0000, v235
	v_lshlrev_b32_e32 v36, 16, v235
	v_lshlrev_b32_e32 v30, 16, v238
	v_and_b32_e32 v13, 0xffff0000, v238
	v_lshlrev_b32_e32 v34, 16, v239
	v_and_b32_e32 v37, 0xffff0000, v239
	v_lshlrev_b32_e32 v16, 16, v243
	v_and_b32_e32 v17, 0xffff0000, v243
	v_mul_f32_e32 v5, 0x3fb8aa3b, v5
	v_exp_f32_e32 v21, v9
	v_exp_f32_e32 v20, v20
	v_exp_f32_e32 v5, v5
	v_and_b32_e32 v25, 0xffff0000, v232
	v_lshlrev_b32_e32 v10, 16, v232
	v_add_f32_e32 v9, v21, v20
	v_add_f32_e32 v9, v5, v9
	v_and_b32_e32 v31, 0xffff0000, v234
	v_rcp_f32_e32 v40, v9
	s_nop 0
	v_lshlrev_b32_e32 v12, 16, v234
	v_pk_mul_f32 v[20:21], v[20:21], v[40:41] op_sel_hi:[1,0]
	v_mul_f32_e32 v42, v5, v40
	v_pk_mul_f32 v[10:11], v[20:21], v[10:11] op_sel:[1,0] op_sel_hi:[0,1]
	v_pk_mul_f32 v[28:29], v[20:21], v[28:29] op_sel:[1,0] op_sel_hi:[0,1]
	v_pk_mul_f32 v[12:13], v[20:21], v[12:13] op_sel:[1,0] op_sel_hi:[0,1]
	v_pk_mul_f32 v[36:37], v[20:21], v[36:37] op_sel:[1,0] op_sel_hi:[0,1]
	v_pk_fma_f32 v[10:11], v[20:21], v[24:25], v[10:11]
	v_pk_fma_f32 v[24:25], v[20:21], v[26:27], v[28:29]
	v_pk_fma_f32 v[12:13], v[20:21], v[30:31], v[12:13]
	v_pk_fma_f32 v[20:21], v[20:21], v[34:35], v[36:37]
	v_pk_fma_f32 v[10:11], v[42:43], v[38:39], v[10:11] op_sel_hi:[0,1,1]
	v_pk_fma_f32 v[14:15], v[42:43], v[14:15], v[24:25] op_sel_hi:[0,1,1]
	v_pk_fma_f32 v[12:13], v[42:43], v[18:19], v[12:13] op_sel_hi:[0,1,1]
	v_pk_fma_f32 v[16:17], v[42:43], v[16:17], v[20:21] op_sel_hi:[0,1,1]
	v_cvt_pk_bf16_f32 v10, v10, v11
	v_cvt_pk_bf16_f32 v11, v14, v15
	v_cvt_pk_bf16_f32 v12, v12, v13
	v_cvt_pk_bf16_f32 v13, v16, v17
	v_add_u32_e32 v8, 0x70000, v7
	global_store_dwordx4 v8, v[10:13], s[8:9] offset:1024
	s_waitcnt vmcnt(0)
	s_barrier
	s_mov_b64 s[0:1], exec
	v_readlane_b32 s2, v254, 29
	v_readlane_b32 s3, v254, 30
	s_and_b64 s[2:3], s[0:1], s[2:3]
	s_mov_b64 exec, s[2:3]
	s_cbranch_execz .LBB0_605
	s_andn2_b64 vcc, exec, s[42:43]
	s_cbranch_vccnz .LBB0_594
	buffer_wbl2 sc1
	s_waitcnt vmcnt(0)
	s_waitcnt vmcnt(0)
